# 8-phase K loops without the per-phase s_setprio flips
# speedup vs baseline: 1.0342x; 1.0106x over previous
.LBB0_236:
	ds_read_b128 v[144:147], v160
	ds_read_b128 v[148:151], v161
	ds_read_b128 v[178:181], v163
	ds_read_b128 v[182:185], v164
	s_add_i32 s14, s2, 2
	s_add_u32 s8, s6, 0x80
	s_addc_u32 s3, s7, 0
	s_cmp_eq_u32 s56, s2
	s_cselect_b32 s2, s62, s8
	s_cselect_b32 s3, s63, s3
	s_cselect_b32 s9, s1, s11
	s_cselect_b32 s8, s0, s10
	s_mov_b32 m0, s61
	v_lshl_add_u64 v[152:153], s[6:7], 0, v[136:137]
	ds_read_b128 v[186:189], v158
	ds_read_b128 v[190:193], v158 offset:1024
	ds_read_b128 v[194:197], v158 offset:2048
	ds_read_b128 v[198:201], v158 offset:3072
	ds_read_b128 v[202:205], v158 offset:4096
	ds_read_b128 v[206:209], v158 offset:5120
	ds_read_b128 v[210:213], v158 offset:6144
	ds_read_b128 v[214:217], v158 offset:7168
	global_load_lds_dwordx4 v[152:153], off
	v_lshl_add_u64 v[152:153], s[6:7], 0, v[138:139]
	s_mov_b32 m0, s64
	s_nop 0
	global_load_lds_dwordx4 v[152:153], off
	s_waitcnt lgkmcnt(8)
	s_barrier
	s_waitcnt lgkmcnt(0)
	s_waitcnt lgkmcnt(0)
	v_mfma_f32_16x16x32_bf16 v[126:129], v[144:147], v[186:189], v[126:129]
	v_mfma_f32_16x16x32_bf16 v[122:125], v[178:181], v[186:189], v[122:125]
	v_mfma_f32_16x16x32_bf16 v[110:113], v[144:147], v[194:197], v[110:113]
	v_mfma_f32_16x16x32_bf16 v[106:109], v[178:181], v[194:197], v[106:109]
	v_mfma_f32_16x16x32_bf16 v[94:97], v[144:147], v[202:205], v[94:97]
	v_mfma_f32_16x16x32_bf16 v[90:93], v[178:181], v[202:205], v[90:93]
	v_mfma_f32_16x16x32_bf16 v[78:81], v[144:147], v[210:213], v[78:81]
	v_mfma_f32_16x16x32_bf16 v[74:77], v[178:181], v[210:213], v[74:77]
	v_mfma_f32_16x16x32_bf16 v[126:129], v[148:151], v[190:193], v[126:129]
	v_mfma_f32_16x16x32_bf16 v[122:125], v[182:185], v[190:193], v[122:125]
	v_mfma_f32_16x16x32_bf16 v[110:113], v[148:151], v[198:201], v[110:113]
	v_mfma_f32_16x16x32_bf16 v[106:109], v[182:185], v[198:201], v[106:109]
	v_mfma_f32_16x16x32_bf16 v[94:97], v[148:151], v[206:209], v[94:97]
	v_mfma_f32_16x16x32_bf16 v[90:93], v[182:185], v[206:209], v[90:93]
	v_mfma_f32_16x16x32_bf16 v[78:81], v[148:151], v[214:217], v[78:81]
	v_mfma_f32_16x16x32_bf16 v[74:77], v[182:185], v[214:217], v[74:77]
	s_barrier
	s_mov_b32 m0, s30
	v_lshl_add_u64 v[152:153], s[8:9], 0, v[130:131]
	ds_read_b128 v[218:221], v165
	ds_read_b128 v[222:225], v166
	ds_read_b128 v[226:229], v167
	ds_read_b128 v[230:233], v168
	global_load_lds_dwordx4 v[152:153], off
	v_lshl_add_u64 v[234:235], s[8:9], 0, v[132:133]
	s_mov_b32 m0, s31
	s_nop 0
	global_load_lds_dwordx4 v[234:235], off
	s_barrier
	s_waitcnt lgkmcnt(0)
	s_waitcnt lgkmcnt(0)
	v_mfma_f32_16x16x32_bf16 v[118:121], v[218:221], v[186:189], v[118:121]
	v_mfma_f32_16x16x32_bf16 v[114:117], v[226:229], v[186:189], v[114:117]
	v_mfma_f32_16x16x32_bf16 v[102:105], v[218:221], v[194:197], v[102:105]
	v_mfma_f32_16x16x32_bf16 v[98:101], v[226:229], v[194:197], v[98:101]
	v_mfma_f32_16x16x32_bf16 v[86:89], v[218:221], v[202:205], v[86:89]
	v_mfma_f32_16x16x32_bf16 v[82:85], v[226:229], v[202:205], v[82:85]
	v_mfma_f32_16x16x32_bf16 v[70:73], v[218:221], v[210:213], v[70:73]
	v_mfma_f32_16x16x32_bf16 v[66:69], v[226:229], v[210:213], v[66:69]
	v_mfma_f32_16x16x32_bf16 v[118:121], v[222:225], v[190:193], v[118:121]
	v_mfma_f32_16x16x32_bf16 v[114:117], v[230:233], v[190:193], v[114:117]
	v_mfma_f32_16x16x32_bf16 v[102:105], v[222:225], v[198:201], v[102:105]
	v_mfma_f32_16x16x32_bf16 v[98:101], v[230:233], v[198:201], v[98:101]
	v_mfma_f32_16x16x32_bf16 v[86:89], v[222:225], v[206:209], v[86:89]
	v_mfma_f32_16x16x32_bf16 v[82:85], v[230:233], v[206:209], v[82:85]
	v_mfma_f32_16x16x32_bf16 v[70:73], v[222:225], v[214:217], v[70:73]
	v_mfma_f32_16x16x32_bf16 v[66:69], v[230:233], v[214:217], v[66:69]
	s_mov_b32 m0, s29
	v_lshl_add_u64 v[236:237], s[2:3], 0, v[130:131]
	s_barrier
	ds_read_b128 v[186:189], v158 offset:16384
	ds_read_b128 v[190:193], v158 offset:17408
	ds_read_b128 v[194:197], v158 offset:18432
	ds_read_b128 v[198:201], v158 offset:19456
	ds_read_b128 v[202:205], v158 offset:20480
	ds_read_b128 v[206:209], v158 offset:21504
	ds_read_b128 v[210:213], v158 offset:22528
	ds_read_b128 v[214:217], v158 offset:23552
	global_load_lds_dwordx4 v[236:237], off
	v_lshl_add_u64 v[238:239], s[2:3], 0, v[132:133]
	s_mov_b32 m0, s33
	s_nop 0
	global_load_lds_dwordx4 v[238:239], off
	s_barrier
	s_waitcnt lgkmcnt(0)
	s_waitcnt lgkmcnt(0)
	v_mfma_f32_16x16x32_bf16 v[62:65], v[144:147], v[186:189], v[62:65]
	v_mfma_f32_16x16x32_bf16 v[58:61], v[178:181], v[186:189], v[58:61]
	v_mfma_f32_16x16x32_bf16 v[46:49], v[144:147], v[194:197], v[46:49]
	v_mfma_f32_16x16x32_bf16 v[42:45], v[178:181], v[194:197], v[42:45]
	v_mfma_f32_16x16x32_bf16 v[30:33], v[144:147], v[202:205], v[30:33]
	v_mfma_f32_16x16x32_bf16 v[26:29], v[178:181], v[202:205], v[26:29]
	v_mfma_f32_16x16x32_bf16 v[14:17], v[144:147], v[210:213], v[14:17]
	v_mfma_f32_16x16x32_bf16 v[10:13], v[178:181], v[210:213], v[10:13]
	v_mfma_f32_16x16x32_bf16 v[62:65], v[148:151], v[190:193], v[62:65]
	v_mfma_f32_16x16x32_bf16 v[58:61], v[182:185], v[190:193], v[58:61]
	v_mfma_f32_16x16x32_bf16 v[46:49], v[148:151], v[198:201], v[46:49]
	v_mfma_f32_16x16x32_bf16 v[42:45], v[182:185], v[198:201], v[42:45]
	v_mfma_f32_16x16x32_bf16 v[30:33], v[148:151], v[206:209], v[30:33]
	v_mfma_f32_16x16x32_bf16 v[26:29], v[182:185], v[206:209], v[26:29]
	v_mfma_f32_16x16x32_bf16 v[14:17], v[148:151], v[214:217], v[14:17]
	v_mfma_f32_16x16x32_bf16 v[10:13], v[182:185], v[214:217], v[10:13]
	s_barrier
	s_add_u32 s8, s8, s18
	s_addc_u32 s9, s9, s19
	s_mov_b32 m0, s34
	v_lshl_add_u64 v[240:241], s[8:9], 0, v[130:131]
	global_load_lds_dwordx4 v[240:241], off
	v_lshl_add_u64 v[242:243], s[8:9], 0, v[132:133]
	s_mov_b32 m0, s35
	s_nop 0
	global_load_lds_dwordx4 v[242:243], off
	s_waitcnt vmcnt(6)
	s_barrier
	v_mfma_f32_16x16x32_bf16 v[54:57], v[218:221], v[186:189], v[54:57]
	v_mfma_f32_16x16x32_bf16 v[50:53], v[226:229], v[186:189], v[50:53]
	v_mfma_f32_16x16x32_bf16 v[38:41], v[218:221], v[194:197], v[38:41]
	v_mfma_f32_16x16x32_bf16 v[34:37], v[226:229], v[194:197], v[34:37]
	v_mfma_f32_16x16x32_bf16 v[22:25], v[218:221], v[202:205], v[22:25]
	v_mfma_f32_16x16x32_bf16 v[18:21], v[226:229], v[202:205], v[18:21]
	v_mfma_f32_16x16x32_bf16 v[6:9], v[218:221], v[210:213], v[6:9]
	v_mfma_f32_16x16x32_bf16 v[2:5], v[226:229], v[210:213], v[2:5]
	v_mfma_f32_16x16x32_bf16 v[54:57], v[222:225], v[190:193], v[54:57]
	v_mfma_f32_16x16x32_bf16 v[50:53], v[230:233], v[190:193], v[50:53]
	v_mfma_f32_16x16x32_bf16 v[38:41], v[222:225], v[198:201], v[38:41]
	v_mfma_f32_16x16x32_bf16 v[34:37], v[230:233], v[198:201], v[34:37]
	v_mfma_f32_16x16x32_bf16 v[22:25], v[222:225], v[206:209], v[22:25]
	v_mfma_f32_16x16x32_bf16 v[18:21], v[230:233], v[206:209], v[18:21]
	v_mfma_f32_16x16x32_bf16 v[6:9], v[222:225], v[214:217], v[6:9]
	v_mfma_f32_16x16x32_bf16 v[2:5], v[230:233], v[214:217], v[2:5]
	s_barrier
	ds_read_b128 v[144:147], v169
	ds_read_b128 v[148:151], v170
	ds_read_b128 v[178:181], v171
	ds_read_b128 v[182:185], v172
	s_add_u32 s2, s2, s18
	s_addc_u32 s3, s3, s19
	s_mov_b32 m0, s38
	v_lshl_add_u64 v[218:219], s[2:3], 0, v[130:131]
	ds_read_b128 v[186:189], v158 offset:32768
	ds_read_b128 v[190:193], v158 offset:33792
	ds_read_b128 v[194:197], v158 offset:34816
	ds_read_b128 v[198:201], v158 offset:35840
	ds_read_b128 v[202:205], v158 offset:36864
	ds_read_b128 v[206:209], v158 offset:37888
	ds_read_b128 v[210:213], v158 offset:38912
	ds_read_b128 v[214:217], v158 offset:39936
	global_load_lds_dwordx4 v[218:219], off
	v_lshl_add_u64 v[218:219], s[2:3], 0, v[132:133]
	s_mov_b32 m0, s39
	s_nop 0
	global_load_lds_dwordx4 v[218:219], off
	s_waitcnt lgkmcnt(8)
	s_barrier
	s_waitcnt lgkmcnt(0)
	s_waitcnt lgkmcnt(0)
	v_mfma_f32_16x16x32_bf16 v[126:129], v[144:147], v[186:189], v[126:129]
	v_mfma_f32_16x16x32_bf16 v[122:125], v[178:181], v[186:189], v[122:125]
	v_mfma_f32_16x16x32_bf16 v[110:113], v[144:147], v[194:197], v[110:113]
	v_mfma_f32_16x16x32_bf16 v[106:109], v[178:181], v[194:197], v[106:109]
	v_mfma_f32_16x16x32_bf16 v[94:97], v[144:147], v[202:205], v[94:97]
	v_mfma_f32_16x16x32_bf16 v[90:93], v[178:181], v[202:205], v[90:93]
	v_mfma_f32_16x16x32_bf16 v[78:81], v[144:147], v[210:213], v[78:81]
	v_mfma_f32_16x16x32_bf16 v[74:77], v[178:181], v[210:213], v[74:77]
	v_mfma_f32_16x16x32_bf16 v[126:129], v[148:151], v[190:193], v[126:129]
	v_mfma_f32_16x16x32_bf16 v[122:125], v[182:185], v[190:193], v[122:125]
	v_mfma_f32_16x16x32_bf16 v[110:113], v[148:151], v[198:201], v[110:113]
	v_mfma_f32_16x16x32_bf16 v[106:109], v[182:185], v[198:201], v[106:109]
	v_mfma_f32_16x16x32_bf16 v[94:97], v[148:151], v[206:209], v[94:97]
	v_mfma_f32_16x16x32_bf16 v[90:93], v[182:185], v[206:209], v[90:93]
	v_mfma_f32_16x16x32_bf16 v[78:81], v[148:151], v[214:217], v[78:81]
	v_mfma_f32_16x16x32_bf16 v[74:77], v[182:185], v[214:217], v[74:77]
	s_barrier
	s_mov_b32 m0, s41
	v_lshl_add_u64 v[152:153], v[152:153], 0, s[22:23]
	ds_read_b128 v[218:221], v173
	ds_read_b128 v[222:225], v174
	ds_read_b128 v[226:229], v175
	ds_read_b128 v[230:233], v176
	global_load_lds_dwordx4 v[152:153], off
	v_lshl_add_u64 v[152:153], v[234:235], 0, s[22:23]
	s_mov_b32 m0, s42
	s_nop 0
	global_load_lds_dwordx4 v[152:153], off
	s_barrier
	s_waitcnt lgkmcnt(0)
	s_waitcnt lgkmcnt(0)
	v_mfma_f32_16x16x32_bf16 v[118:121], v[218:221], v[186:189], v[118:121]
	v_mfma_f32_16x16x32_bf16 v[114:117], v[226:229], v[186:189], v[114:117]
	v_mfma_f32_16x16x32_bf16 v[102:105], v[218:221], v[194:197], v[102:105]
	v_mfma_f32_16x16x32_bf16 v[98:101], v[226:229], v[194:197], v[98:101]
	v_mfma_f32_16x16x32_bf16 v[86:89], v[218:221], v[202:205], v[86:89]
	v_mfma_f32_16x16x32_bf16 v[82:85], v[226:229], v[202:205], v[82:85]
	v_mfma_f32_16x16x32_bf16 v[70:73], v[218:221], v[210:213], v[70:73]
	v_mfma_f32_16x16x32_bf16 v[66:69], v[226:229], v[210:213], v[66:69]
	v_mfma_f32_16x16x32_bf16 v[118:121], v[222:225], v[190:193], v[118:121]
	v_mfma_f32_16x16x32_bf16 v[114:117], v[230:233], v[190:193], v[114:117]
	v_mfma_f32_16x16x32_bf16 v[102:105], v[222:225], v[198:201], v[102:105]
	v_mfma_f32_16x16x32_bf16 v[98:101], v[230:233], v[198:201], v[98:101]
	v_mfma_f32_16x16x32_bf16 v[86:89], v[222:225], v[206:209], v[86:89]
	v_mfma_f32_16x16x32_bf16 v[82:85], v[230:233], v[206:209], v[82:85]
	v_mfma_f32_16x16x32_bf16 v[70:73], v[222:225], v[214:217], v[70:73]
	v_mfma_f32_16x16x32_bf16 v[66:69], v[230:233], v[214:217], v[66:69]
	s_mov_b32 m0, s43
	v_lshl_add_u64 v[152:153], v[236:237], 0, s[22:23]
	s_barrier
	ds_read_b128 v[186:189], v158 offset:49152
	ds_read_b128 v[190:193], v158 offset:50176
	ds_read_b128 v[194:197], v158 offset:51200
	ds_read_b128 v[198:201], v158 offset:52224
	ds_read_b128 v[202:205], v158 offset:53248
	ds_read_b128 v[206:209], v158 offset:54272
	ds_read_b128 v[210:213], v158 offset:55296
	ds_read_b128 v[214:217], v158 offset:56320
	global_load_lds_dwordx4 v[152:153], off
	v_lshl_add_u64 v[152:153], v[238:239], 0, s[22:23]
	s_mov_b32 m0, s48
	s_nop 0
	global_load_lds_dwordx4 v[152:153], off
	s_barrier
	s_waitcnt lgkmcnt(0)
	s_waitcnt lgkmcnt(0)
	v_mfma_f32_16x16x32_bf16 v[62:65], v[144:147], v[186:189], v[62:65]
	v_mfma_f32_16x16x32_bf16 v[58:61], v[178:181], v[186:189], v[58:61]
	v_mfma_f32_16x16x32_bf16 v[46:49], v[144:147], v[194:197], v[46:49]
	v_mfma_f32_16x16x32_bf16 v[42:45], v[178:181], v[194:197], v[42:45]
	v_mfma_f32_16x16x32_bf16 v[30:33], v[144:147], v[202:205], v[30:33]
	v_mfma_f32_16x16x32_bf16 v[26:29], v[178:181], v[202:205], v[26:29]
	v_mfma_f32_16x16x32_bf16 v[14:17], v[144:147], v[210:213], v[14:17]
	v_mfma_f32_16x16x32_bf16 v[10:13], v[178:181], v[210:213], v[10:13]
	v_mfma_f32_16x16x32_bf16 v[62:65], v[148:151], v[190:193], v[62:65]
	v_mfma_f32_16x16x32_bf16 v[58:61], v[182:185], v[190:193], v[58:61]
	v_mfma_f32_16x16x32_bf16 v[46:49], v[148:151], v[198:201], v[46:49]
	v_mfma_f32_16x16x32_bf16 v[42:45], v[182:185], v[198:201], v[42:45]
	v_mfma_f32_16x16x32_bf16 v[30:33], v[148:151], v[206:209], v[30:33]
	v_mfma_f32_16x16x32_bf16 v[26:29], v[182:185], v[206:209], v[26:29]
	v_mfma_f32_16x16x32_bf16 v[14:17], v[148:151], v[214:217], v[14:17]
	v_mfma_f32_16x16x32_bf16 v[10:13], v[182:185], v[214:217], v[10:13]
	s_barrier
	s_mov_b32 m0, s49
	v_lshl_add_u64 v[144:145], v[240:241], 0, s[22:23]
	global_load_lds_dwordx4 v[144:145], off
	v_lshl_add_u64 v[144:145], v[242:243], 0, s[22:23]
	s_mov_b32 m0, s50
	s_nop 0
	global_load_lds_dwordx4 v[144:145], off
	s_waitcnt vmcnt(6)
	s_barrier
	v_mfma_f32_16x16x32_bf16 v[54:57], v[218:221], v[186:189], v[54:57]
	v_mfma_f32_16x16x32_bf16 v[50:53], v[226:229], v[186:189], v[50:53]
	v_mfma_f32_16x16x32_bf16 v[38:41], v[218:221], v[194:197], v[38:41]
	v_mfma_f32_16x16x32_bf16 v[34:37], v[226:229], v[194:197], v[34:37]
	v_mfma_f32_16x16x32_bf16 v[22:25], v[218:221], v[202:205], v[22:25]
	v_mfma_f32_16x16x32_bf16 v[18:21], v[226:229], v[202:205], v[18:21]
	v_mfma_f32_16x16x32_bf16 v[6:9], v[218:221], v[210:213], v[6:9]
	v_mfma_f32_16x16x32_bf16 v[2:5], v[226:229], v[210:213], v[2:5]
	v_mfma_f32_16x16x32_bf16 v[54:57], v[222:225], v[190:193], v[54:57]
	v_mfma_f32_16x16x32_bf16 v[50:53], v[230:233], v[190:193], v[50:53]
	v_mfma_f32_16x16x32_bf16 v[38:41], v[222:225], v[198:201], v[38:41]
	v_mfma_f32_16x16x32_bf16 v[34:37], v[230:233], v[198:201], v[34:37]
	v_mfma_f32_16x16x32_bf16 v[22:25], v[222:225], v[206:209], v[22:25]
	v_mfma_f32_16x16x32_bf16 v[18:21], v[230:233], v[206:209], v[18:21]
	v_mfma_f32_16x16x32_bf16 v[6:9], v[222:225], v[214:217], v[6:9]
	v_mfma_f32_16x16x32_bf16 v[2:5], v[230:233], v[214:217], v[2:5]
	s_add_u32 s6, s6, 0x100
	s_addc_u32 s7, s7, 0
	s_add_u32 s10, s10, 0x100
	s_addc_u32 s11, s11, 0
	s_cmp_ge_i32 s14, s51
	s_mov_b32 s2, s14
	s_barrier
	s_cbranch_scc0 .LBB0_236

.LBB0_997:
	ds_read_b128 v[142:145], v168
	ds_read_b128 v[146:149], v169
	ds_read_b128 v[150:153], v170
	ds_read_b128 v[154:157], v171
	s_add_i32 s57, s2, 2
	s_add_u32 s26, s24, 0x80
	s_addc_u32 s3, s25, 0
	s_cmp_eq_u32 s46, s2
	s_cselect_b32 s2, s10, s26
	s_cselect_b32 s3, s11, s3
	s_cselect_b32 s27, s1, s37
	s_cselect_b32 s26, s0, s36
	s_mov_b32 m0, s51
	v_lshl_add_u64 v[158:159], s[24:25], 0, v[134:135]
	ds_read_b128 v[186:189], v166
	ds_read_b128 v[190:193], v166 offset:1024
	ds_read_b128 v[194:197], v166 offset:2048
	ds_read_b128 v[198:201], v166 offset:3072
	ds_read_b128 v[202:205], v166 offset:4096
	ds_read_b128 v[206:209], v166 offset:5120
	ds_read_b128 v[210:213], v166 offset:6144
	ds_read_b128 v[214:217], v166 offset:7168
	global_load_lds_dwordx4 v[158:159], off
	v_lshl_add_u64 v[158:159], s[24:25], 0, v[136:137]
	s_mov_b32 m0, s52
	s_nop 0
	global_load_lds_dwordx4 v[158:159], off
	s_waitcnt lgkmcnt(8)
	s_barrier
	s_waitcnt lgkmcnt(0)
	s_waitcnt lgkmcnt(0)
	v_mfma_f32_16x16x32_bf16 v[126:129], v[142:145], v[186:189], v[126:129]
	v_mfma_f32_16x16x32_bf16 v[122:125], v[150:153], v[186:189], v[122:125]
	v_mfma_f32_16x16x32_bf16 v[110:113], v[142:145], v[194:197], v[110:113]
	v_mfma_f32_16x16x32_bf16 v[106:109], v[150:153], v[194:197], v[106:109]
	v_mfma_f32_16x16x32_bf16 v[94:97], v[142:145], v[202:205], v[94:97]
	v_mfma_f32_16x16x32_bf16 v[90:93], v[150:153], v[202:205], v[90:93]
	v_mfma_f32_16x16x32_bf16 v[78:81], v[142:145], v[210:213], v[78:81]
	v_mfma_f32_16x16x32_bf16 v[74:77], v[150:153], v[210:213], v[74:77]
	v_mfma_f32_16x16x32_bf16 v[126:129], v[146:149], v[190:193], v[126:129]
	v_mfma_f32_16x16x32_bf16 v[122:125], v[154:157], v[190:193], v[122:125]
	v_mfma_f32_16x16x32_bf16 v[110:113], v[146:149], v[198:201], v[110:113]
	v_mfma_f32_16x16x32_bf16 v[106:109], v[154:157], v[198:201], v[106:109]
	v_mfma_f32_16x16x32_bf16 v[94:97], v[146:149], v[206:209], v[94:97]
	v_mfma_f32_16x16x32_bf16 v[90:93], v[154:157], v[206:209], v[90:93]
	v_mfma_f32_16x16x32_bf16 v[78:81], v[146:149], v[214:217], v[78:81]
	v_mfma_f32_16x16x32_bf16 v[74:77], v[154:157], v[214:217], v[74:77]
	s_barrier
	s_mov_b32 m0, s29
	v_lshl_add_u64 v[158:159], s[26:27], 0, v[130:131]
	ds_read_b128 v[218:221], v172
	ds_read_b128 v[222:225], v173
	ds_read_b128 v[226:229], v174
	ds_read_b128 v[230:233], v175
	global_load_lds_dwordx4 v[158:159], off
	v_lshl_add_u64 v[234:235], s[26:27], 0, v[132:133]
	s_mov_b32 m0, s30
	s_nop 0
	global_load_lds_dwordx4 v[234:235], off
	s_barrier
	s_waitcnt lgkmcnt(0)
	s_waitcnt lgkmcnt(0)
	v_mfma_f32_16x16x32_bf16 v[118:121], v[218:221], v[186:189], v[118:121]
	v_mfma_f32_16x16x32_bf16 v[114:117], v[226:229], v[186:189], v[114:117]
	v_mfma_f32_16x16x32_bf16 v[102:105], v[218:221], v[194:197], v[102:105]
	v_mfma_f32_16x16x32_bf16 v[98:101], v[226:229], v[194:197], v[98:101]
	v_mfma_f32_16x16x32_bf16 v[86:89], v[218:221], v[202:205], v[86:89]
	v_mfma_f32_16x16x32_bf16 v[82:85], v[226:229], v[202:205], v[82:85]
	v_mfma_f32_16x16x32_bf16 v[70:73], v[218:221], v[210:213], v[70:73]
	v_mfma_f32_16x16x32_bf16 v[66:69], v[226:229], v[210:213], v[66:69]
	v_mfma_f32_16x16x32_bf16 v[118:121], v[222:225], v[190:193], v[118:121]
	v_mfma_f32_16x16x32_bf16 v[114:117], v[230:233], v[190:193], v[114:117]
	v_mfma_f32_16x16x32_bf16 v[102:105], v[222:225], v[198:201], v[102:105]
	v_mfma_f32_16x16x32_bf16 v[98:101], v[230:233], v[198:201], v[98:101]
	v_mfma_f32_16x16x32_bf16 v[86:89], v[222:225], v[206:209], v[86:89]
	v_mfma_f32_16x16x32_bf16 v[82:85], v[230:233], v[206:209], v[82:85]
	v_mfma_f32_16x16x32_bf16 v[70:73], v[222:225], v[214:217], v[70:73]
	v_mfma_f32_16x16x32_bf16 v[66:69], v[230:233], v[214:217], v[66:69]
	s_mov_b32 m0, s28
	v_lshl_add_u64 v[236:237], s[2:3], 0, v[130:131]
	s_barrier
	ds_read_b128 v[186:189], v166 offset:16384
	ds_read_b128 v[190:193], v166 offset:17408
	ds_read_b128 v[194:197], v166 offset:18432
	ds_read_b128 v[198:201], v166 offset:19456
	ds_read_b128 v[202:205], v166 offset:20480
	ds_read_b128 v[206:209], v166 offset:21504
	ds_read_b128 v[210:213], v166 offset:22528
	ds_read_b128 v[214:217], v166 offset:23552
	global_load_lds_dwordx4 v[236:237], off
	v_lshl_add_u64 v[238:239], s[2:3], 0, v[132:133]
	s_mov_b32 m0, s31
	s_nop 0
	global_load_lds_dwordx4 v[238:239], off
	s_barrier
	s_waitcnt lgkmcnt(0)
	s_waitcnt lgkmcnt(0)
	v_mfma_f32_16x16x32_bf16 v[62:65], v[142:145], v[186:189], v[62:65]
	v_mfma_f32_16x16x32_bf16 v[58:61], v[150:153], v[186:189], v[58:61]
	v_mfma_f32_16x16x32_bf16 v[46:49], v[142:145], v[194:197], v[46:49]
	v_mfma_f32_16x16x32_bf16 v[42:45], v[150:153], v[194:197], v[42:45]
	v_mfma_f32_16x16x32_bf16 v[30:33], v[142:145], v[202:205], v[30:33]
	v_mfma_f32_16x16x32_bf16 v[26:29], v[150:153], v[202:205], v[26:29]
	v_mfma_f32_16x16x32_bf16 v[14:17], v[142:145], v[210:213], v[14:17]
	v_mfma_f32_16x16x32_bf16 v[10:13], v[150:153], v[210:213], v[10:13]
	v_mfma_f32_16x16x32_bf16 v[62:65], v[146:149], v[190:193], v[62:65]
	v_mfma_f32_16x16x32_bf16 v[58:61], v[154:157], v[190:193], v[58:61]
	v_mfma_f32_16x16x32_bf16 v[46:49], v[146:149], v[198:201], v[46:49]
	v_mfma_f32_16x16x32_bf16 v[42:45], v[154:157], v[198:201], v[42:45]
	v_mfma_f32_16x16x32_bf16 v[30:33], v[146:149], v[206:209], v[30:33]
	v_mfma_f32_16x16x32_bf16 v[26:29], v[154:157], v[206:209], v[26:29]
	v_mfma_f32_16x16x32_bf16 v[14:17], v[146:149], v[214:217], v[14:17]
	v_mfma_f32_16x16x32_bf16 v[10:13], v[154:157], v[214:217], v[10:13]
	s_barrier
	s_add_u32 s26, s26, s16
	s_addc_u32 s27, s27, s17
	s_mov_b32 m0, s33
	v_lshl_add_u64 v[240:241], s[26:27], 0, v[130:131]
	global_load_lds_dwordx4 v[240:241], off
	v_lshl_add_u64 v[242:243], s[26:27], 0, v[132:133]
	s_mov_b32 m0, s34
	s_nop 0
	global_load_lds_dwordx4 v[242:243], off
	s_waitcnt vmcnt(6)
	s_barrier
	v_mfma_f32_16x16x32_bf16 v[54:57], v[218:221], v[186:189], v[54:57]
	v_mfma_f32_16x16x32_bf16 v[50:53], v[226:229], v[186:189], v[50:53]
	v_mfma_f32_16x16x32_bf16 v[38:41], v[218:221], v[194:197], v[38:41]
	v_mfma_f32_16x16x32_bf16 v[34:37], v[226:229], v[194:197], v[34:37]
	v_mfma_f32_16x16x32_bf16 v[22:25], v[218:221], v[202:205], v[22:25]
	v_mfma_f32_16x16x32_bf16 v[18:21], v[226:229], v[202:205], v[18:21]
	v_mfma_f32_16x16x32_bf16 v[6:9], v[218:221], v[210:213], v[6:9]
	v_mfma_f32_16x16x32_bf16 v[2:5], v[226:229], v[210:213], v[2:5]
	v_mfma_f32_16x16x32_bf16 v[54:57], v[222:225], v[190:193], v[54:57]
	v_mfma_f32_16x16x32_bf16 v[50:53], v[230:233], v[190:193], v[50:53]
	v_mfma_f32_16x16x32_bf16 v[38:41], v[222:225], v[198:201], v[38:41]
	v_mfma_f32_16x16x32_bf16 v[34:37], v[230:233], v[198:201], v[34:37]
	v_mfma_f32_16x16x32_bf16 v[22:25], v[222:225], v[206:209], v[22:25]
	v_mfma_f32_16x16x32_bf16 v[18:21], v[230:233], v[206:209], v[18:21]
	v_mfma_f32_16x16x32_bf16 v[6:9], v[222:225], v[214:217], v[6:9]
	v_mfma_f32_16x16x32_bf16 v[2:5], v[230:233], v[214:217], v[2:5]
	s_barrier
	ds_read_b128 v[142:145], v176
	ds_read_b128 v[146:149], v177
	ds_read_b128 v[150:153], v178
	ds_read_b128 v[154:157], v179
	s_add_u32 s2, s2, s16
	s_addc_u32 s3, s3, s17
	s_mov_b32 m0, s35
	v_lshl_add_u64 v[218:219], s[2:3], 0, v[130:131]
	ds_read_b128 v[186:189], v166 offset:32768
	ds_read_b128 v[190:193], v166 offset:33792
	ds_read_b128 v[194:197], v166 offset:34816
	ds_read_b128 v[198:201], v166 offset:35840
	ds_read_b128 v[202:205], v166 offset:36864
	ds_read_b128 v[206:209], v166 offset:37888
	ds_read_b128 v[210:213], v166 offset:38912
	ds_read_b128 v[214:217], v166 offset:39936
	global_load_lds_dwordx4 v[218:219], off
	v_lshl_add_u64 v[218:219], s[2:3], 0, v[132:133]
	s_mov_b32 m0, s38
	s_nop 0
	global_load_lds_dwordx4 v[218:219], off
	s_waitcnt lgkmcnt(8)
	s_barrier
	s_waitcnt lgkmcnt(0)
	s_waitcnt lgkmcnt(0)
	v_mfma_f32_16x16x32_bf16 v[126:129], v[142:145], v[186:189], v[126:129]
	v_mfma_f32_16x16x32_bf16 v[122:125], v[150:153], v[186:189], v[122:125]
	v_mfma_f32_16x16x32_bf16 v[110:113], v[142:145], v[194:197], v[110:113]
	v_mfma_f32_16x16x32_bf16 v[106:109], v[150:153], v[194:197], v[106:109]
	v_mfma_f32_16x16x32_bf16 v[94:97], v[142:145], v[202:205], v[94:97]
	v_mfma_f32_16x16x32_bf16 v[90:93], v[150:153], v[202:205], v[90:93]
	v_mfma_f32_16x16x32_bf16 v[78:81], v[142:145], v[210:213], v[78:81]
	v_mfma_f32_16x16x32_bf16 v[74:77], v[150:153], v[210:213], v[74:77]
	v_mfma_f32_16x16x32_bf16 v[126:129], v[146:149], v[190:193], v[126:129]
	v_mfma_f32_16x16x32_bf16 v[122:125], v[154:157], v[190:193], v[122:125]
	v_mfma_f32_16x16x32_bf16 v[110:113], v[146:149], v[198:201], v[110:113]
	v_mfma_f32_16x16x32_bf16 v[106:109], v[154:157], v[198:201], v[106:109]
	v_mfma_f32_16x16x32_bf16 v[94:97], v[146:149], v[206:209], v[94:97]
	v_mfma_f32_16x16x32_bf16 v[90:93], v[154:157], v[206:209], v[90:93]
	v_mfma_f32_16x16x32_bf16 v[78:81], v[146:149], v[214:217], v[78:81]
	v_mfma_f32_16x16x32_bf16 v[74:77], v[154:157], v[214:217], v[74:77]
	s_barrier
	s_mov_b32 m0, s39
	v_lshl_add_u64 v[158:159], v[158:159], 0, s[20:21]
	ds_read_b128 v[218:221], v180
	ds_read_b128 v[222:225], v181
	ds_read_b128 v[226:229], v182
	ds_read_b128 v[230:233], v183
	global_load_lds_dwordx4 v[158:159], off
	v_lshl_add_u64 v[158:159], v[234:235], 0, s[20:21]
	s_mov_b32 m0, s40
	s_nop 0
	global_load_lds_dwordx4 v[158:159], off
	s_barrier
	s_waitcnt lgkmcnt(0)
	s_waitcnt lgkmcnt(0)
	v_mfma_f32_16x16x32_bf16 v[118:121], v[218:221], v[186:189], v[118:121]
	v_mfma_f32_16x16x32_bf16 v[114:117], v[226:229], v[186:189], v[114:117]
	v_mfma_f32_16x16x32_bf16 v[102:105], v[218:221], v[194:197], v[102:105]
	v_mfma_f32_16x16x32_bf16 v[98:101], v[226:229], v[194:197], v[98:101]
	v_mfma_f32_16x16x32_bf16 v[86:89], v[218:221], v[202:205], v[86:89]
	v_mfma_f32_16x16x32_bf16 v[82:85], v[226:229], v[202:205], v[82:85]
	v_mfma_f32_16x16x32_bf16 v[70:73], v[218:221], v[210:213], v[70:73]
	v_mfma_f32_16x16x32_bf16 v[66:69], v[226:229], v[210:213], v[66:69]
	v_mfma_f32_16x16x32_bf16 v[118:121], v[222:225], v[190:193], v[118:121]
	v_mfma_f32_16x16x32_bf16 v[114:117], v[230:233], v[190:193], v[114:117]
	v_mfma_f32_16x16x32_bf16 v[102:105], v[222:225], v[198:201], v[102:105]
	v_mfma_f32_16x16x32_bf16 v[98:101], v[230:233], v[198:201], v[98:101]
	v_mfma_f32_16x16x32_bf16 v[86:89], v[222:225], v[206:209], v[86:89]
	v_mfma_f32_16x16x32_bf16 v[82:85], v[230:233], v[206:209], v[82:85]
	v_mfma_f32_16x16x32_bf16 v[70:73], v[222:225], v[214:217], v[70:73]
	v_mfma_f32_16x16x32_bf16 v[66:69], v[230:233], v[214:217], v[66:69]
	s_mov_b32 m0, s41
	v_lshl_add_u64 v[158:159], v[236:237], 0, s[20:21]
	s_barrier
	ds_read_b128 v[186:189], v166 offset:49152
	ds_read_b128 v[190:193], v166 offset:50176
	ds_read_b128 v[194:197], v166 offset:51200
	ds_read_b128 v[198:201], v166 offset:52224
	ds_read_b128 v[202:205], v166 offset:53248
	ds_read_b128 v[206:209], v166 offset:54272
	ds_read_b128 v[210:213], v166 offset:55296
	ds_read_b128 v[214:217], v166 offset:56320
	global_load_lds_dwordx4 v[158:159], off
	v_lshl_add_u64 v[158:159], v[238:239], 0, s[20:21]
	s_mov_b32 m0, s42
	s_nop 0
	global_load_lds_dwordx4 v[158:159], off
	s_barrier
	s_waitcnt lgkmcnt(0)
	s_waitcnt lgkmcnt(0)
	v_mfma_f32_16x16x32_bf16 v[62:65], v[142:145], v[186:189], v[62:65]
	v_mfma_f32_16x16x32_bf16 v[58:61], v[150:153], v[186:189], v[58:61]
	v_mfma_f32_16x16x32_bf16 v[46:49], v[142:145], v[194:197], v[46:49]
	v_mfma_f32_16x16x32_bf16 v[42:45], v[150:153], v[194:197], v[42:45]
	v_mfma_f32_16x16x32_bf16 v[30:33], v[142:145], v[202:205], v[30:33]
	v_mfma_f32_16x16x32_bf16 v[26:29], v[150:153], v[202:205], v[26:29]
	v_mfma_f32_16x16x32_bf16 v[14:17], v[142:145], v[210:213], v[14:17]
	v_mfma_f32_16x16x32_bf16 v[10:13], v[150:153], v[210:213], v[10:13]
	v_mfma_f32_16x16x32_bf16 v[62:65], v[146:149], v[190:193], v[62:65]
	v_mfma_f32_16x16x32_bf16 v[58:61], v[154:157], v[190:193], v[58:61]
	v_mfma_f32_16x16x32_bf16 v[46:49], v[146:149], v[198:201], v[46:49]
	v_mfma_f32_16x16x32_bf16 v[42:45], v[154:157], v[198:201], v[42:45]
	v_mfma_f32_16x16x32_bf16 v[30:33], v[146:149], v[206:209], v[30:33]
	v_mfma_f32_16x16x32_bf16 v[26:29], v[154:157], v[206:209], v[26:29]
	v_mfma_f32_16x16x32_bf16 v[14:17], v[146:149], v[214:217], v[14:17]
	v_mfma_f32_16x16x32_bf16 v[10:13], v[154:157], v[214:217], v[10:13]
	s_barrier
	s_mov_b32 m0, s43
	v_lshl_add_u64 v[142:143], v[240:241], 0, s[20:21]
	global_load_lds_dwordx4 v[142:143], off
	v_lshl_add_u64 v[142:143], v[242:243], 0, s[20:21]
	s_mov_b32 m0, s44
	s_nop 0
	global_load_lds_dwordx4 v[142:143], off
	s_waitcnt vmcnt(6)
	s_barrier
	v_mfma_f32_16x16x32_bf16 v[54:57], v[218:221], v[186:189], v[54:57]
	v_mfma_f32_16x16x32_bf16 v[50:53], v[226:229], v[186:189], v[50:53]
	v_mfma_f32_16x16x32_bf16 v[38:41], v[218:221], v[194:197], v[38:41]
	v_mfma_f32_16x16x32_bf16 v[34:37], v[226:229], v[194:197], v[34:37]
	v_mfma_f32_16x16x32_bf16 v[22:25], v[218:221], v[202:205], v[22:25]
	v_mfma_f32_16x16x32_bf16 v[18:21], v[226:229], v[202:205], v[18:21]
	v_mfma_f32_16x16x32_bf16 v[6:9], v[218:221], v[210:213], v[6:9]
	v_mfma_f32_16x16x32_bf16 v[2:5], v[226:229], v[210:213], v[2:5]
	v_mfma_f32_16x16x32_bf16 v[54:57], v[222:225], v[190:193], v[54:57]
	v_mfma_f32_16x16x32_bf16 v[50:53], v[230:233], v[190:193], v[50:53]
	v_mfma_f32_16x16x32_bf16 v[38:41], v[222:225], v[198:201], v[38:41]
	v_mfma_f32_16x16x32_bf16 v[34:37], v[230:233], v[198:201], v[34:37]
	v_mfma_f32_16x16x32_bf16 v[22:25], v[222:225], v[206:209], v[22:25]
	v_mfma_f32_16x16x32_bf16 v[18:21], v[230:233], v[206:209], v[18:21]
	v_mfma_f32_16x16x32_bf16 v[6:9], v[222:225], v[214:217], v[6:9]
	v_mfma_f32_16x16x32_bf16 v[2:5], v[230:233], v[214:217], v[2:5]
	s_add_u32 s24, s24, 0x100
	s_addc_u32 s25, s25, 0
	s_add_u32 s36, s36, 0x100
	s_addc_u32 s37, s37, 0
	s_cmp_ge_i32 s57, s45
	s_mov_b32 s2, s57
	s_barrier
	s_cbranch_scc0 .LBB0_997

.LBB0_1104:
	ds_read_b128 v[122:125], v185
	ds_read_b128 v[126:129], v186
	ds_read_b128 v[138:141], v187
	ds_read_b128 v[142:145], v188
	s_add_i32 s36, s2, 2
	s_add_u32 s26, s0, 0x80
	s_addc_u32 s3, s1, 0
	s_cmp_eq_u32 s58, s2
	s_cselect_b32 s2, s8, s26
	s_cselect_b32 s3, s9, s3
	s_cselect_b32 s27, s55, s29
	s_cselect_b32 s26, s54, s28
	s_mov_b32 m0, s61
	v_lshl_add_u64 v[214:215], s[0:1], 0, v[168:169]
	ds_read_b128 v[146:149], v183
	ds_read_b128 v[150:153], v183 offset:1024
	ds_read_b128 v[154:157], v183 offset:2048
	ds_read_b128 v[158:161], v183 offset:3072
	ds_read_b128 v[176:179], v183 offset:4096
	ds_read_b128 v[202:205], v183 offset:5120
	ds_read_b128 v[206:209], v183 offset:6144
	ds_read_b128 v[210:213], v183 offset:7168
	global_load_lds_dwordx4 v[214:215], off
	v_lshl_add_u64 v[214:215], s[0:1], 0, v[170:171]
	s_mov_b32 m0, s62
	s_nop 0
	global_load_lds_dwordx4 v[214:215], off
	s_waitcnt lgkmcnt(8)
	s_barrier
	s_waitcnt lgkmcnt(0)
	s_waitcnt lgkmcnt(0)
	v_mfma_f32_16x16x32_bf16 v[134:137], v[122:125], v[146:149], v[134:137]
	v_mfma_f32_16x16x32_bf16 v[118:121], v[138:141], v[146:149], v[118:121]
	v_mfma_f32_16x16x32_bf16 v[110:113], v[122:125], v[154:157], v[110:113]
	v_mfma_f32_16x16x32_bf16 v[102:105], v[138:141], v[154:157], v[102:105]
	v_mfma_f32_16x16x32_bf16 v[94:97], v[122:125], v[176:179], v[94:97]
	v_mfma_f32_16x16x32_bf16 v[86:89], v[138:141], v[176:179], v[86:89]
	v_mfma_f32_16x16x32_bf16 v[78:81], v[122:125], v[206:209], v[78:81]
	v_mfma_f32_16x16x32_bf16 v[70:73], v[138:141], v[206:209], v[70:73]
	v_mfma_f32_16x16x32_bf16 v[134:137], v[126:129], v[150:153], v[134:137]
	v_mfma_f32_16x16x32_bf16 v[118:121], v[142:145], v[150:153], v[118:121]
	v_mfma_f32_16x16x32_bf16 v[110:113], v[126:129], v[158:161], v[110:113]
	v_mfma_f32_16x16x32_bf16 v[102:105], v[142:145], v[158:161], v[102:105]
	v_mfma_f32_16x16x32_bf16 v[94:97], v[126:129], v[202:205], v[94:97]
	v_mfma_f32_16x16x32_bf16 v[86:89], v[142:145], v[202:205], v[86:89]
	v_mfma_f32_16x16x32_bf16 v[78:81], v[126:129], v[210:213], v[78:81]
	v_mfma_f32_16x16x32_bf16 v[70:73], v[142:145], v[210:213], v[70:73]
	s_barrier
	s_mov_b32 m0, s35
	v_lshl_add_u64 v[230:231], s[26:27], 0, v[166:167]
	ds_read_b128 v[214:217], v189
	ds_read_b128 v[218:221], v190
	ds_read_b128 v[222:225], v191
	ds_read_b128 v[226:229], v192
	global_load_lds_dwordx4 v[230:231], off
	v_lshl_add_u64 v[232:233], s[26:27], 0, v[164:165]
	s_mov_b32 m0, s38
	s_nop 0
	global_load_lds_dwordx4 v[232:233], off
	s_barrier
	s_waitcnt lgkmcnt(0)
	s_waitcnt lgkmcnt(0)
	v_mfma_f32_16x16x32_bf16 v[130:133], v[214:217], v[146:149], v[130:133]
	v_mfma_f32_16x16x32_bf16 v[114:117], v[222:225], v[146:149], v[114:117]
	v_mfma_f32_16x16x32_bf16 v[106:109], v[214:217], v[154:157], v[106:109]
	v_mfma_f32_16x16x32_bf16 v[98:101], v[222:225], v[154:157], v[98:101]
	v_mfma_f32_16x16x32_bf16 v[90:93], v[214:217], v[176:179], v[90:93]
	v_mfma_f32_16x16x32_bf16 v[82:85], v[222:225], v[176:179], v[82:85]
	v_mfma_f32_16x16x32_bf16 v[74:77], v[214:217], v[206:209], v[74:77]
	v_mfma_f32_16x16x32_bf16 v[66:69], v[222:225], v[206:209], v[66:69]
	v_mfma_f32_16x16x32_bf16 v[130:133], v[218:221], v[150:153], v[130:133]
	v_mfma_f32_16x16x32_bf16 v[114:117], v[226:229], v[150:153], v[114:117]
	v_mfma_f32_16x16x32_bf16 v[106:109], v[218:221], v[158:161], v[106:109]
	v_mfma_f32_16x16x32_bf16 v[98:101], v[226:229], v[158:161], v[98:101]
	v_mfma_f32_16x16x32_bf16 v[90:93], v[218:221], v[202:205], v[90:93]
	v_mfma_f32_16x16x32_bf16 v[82:85], v[226:229], v[202:205], v[82:85]
	v_mfma_f32_16x16x32_bf16 v[74:77], v[218:221], v[210:213], v[74:77]
	v_mfma_f32_16x16x32_bf16 v[66:69], v[226:229], v[210:213], v[66:69]
	s_mov_b32 m0, s31
	v_lshl_add_u64 v[234:235], s[2:3], 0, v[166:167]
	s_barrier
	ds_read_b128 v[146:149], v183 offset:16384
	ds_read_b128 v[150:153], v183 offset:17408
	ds_read_b128 v[154:157], v183 offset:18432
	ds_read_b128 v[158:161], v183 offset:19456
	ds_read_b128 v[176:179], v183 offset:20480
	ds_read_b128 v[202:205], v183 offset:21504
	ds_read_b128 v[206:209], v183 offset:22528
	ds_read_b128 v[210:213], v183 offset:23552
	global_load_lds_dwordx4 v[234:235], off
	v_lshl_add_u64 v[236:237], s[2:3], 0, v[164:165]
	s_mov_b32 m0, s39
	s_nop 0
	global_load_lds_dwordx4 v[236:237], off
	s_barrier
	s_waitcnt lgkmcnt(0)
	s_waitcnt lgkmcnt(0)
	v_mfma_f32_16x16x32_bf16 v[62:65], v[122:125], v[146:149], v[62:65]
	v_mfma_f32_16x16x32_bf16 v[54:57], v[138:141], v[146:149], v[54:57]
	v_mfma_f32_16x16x32_bf16 v[46:49], v[122:125], v[154:157], v[46:49]
	v_mfma_f32_16x16x32_bf16 v[38:41], v[138:141], v[154:157], v[38:41]
	v_mfma_f32_16x16x32_bf16 v[30:33], v[122:125], v[176:179], v[30:33]
	v_mfma_f32_16x16x32_bf16 v[22:25], v[138:141], v[176:179], v[22:25]
	v_mfma_f32_16x16x32_bf16 v[14:17], v[122:125], v[206:209], v[14:17]
	v_mfma_f32_16x16x32_bf16 v[6:9], v[138:141], v[206:209], v[6:9]
	v_mfma_f32_16x16x32_bf16 v[62:65], v[126:129], v[150:153], v[62:65]
	v_mfma_f32_16x16x32_bf16 v[54:57], v[142:145], v[150:153], v[54:57]
	v_mfma_f32_16x16x32_bf16 v[46:49], v[126:129], v[158:161], v[46:49]
	v_mfma_f32_16x16x32_bf16 v[38:41], v[142:145], v[158:161], v[38:41]
	v_mfma_f32_16x16x32_bf16 v[30:33], v[126:129], v[202:205], v[30:33]
	v_mfma_f32_16x16x32_bf16 v[22:25], v[142:145], v[202:205], v[22:25]
	v_mfma_f32_16x16x32_bf16 v[14:17], v[126:129], v[210:213], v[14:17]
	v_mfma_f32_16x16x32_bf16 v[6:9], v[142:145], v[210:213], v[6:9]
	s_barrier
	s_add_u32 s26, s26, s22
	s_addc_u32 s27, s27, s23
	s_mov_b32 m0, s40
	v_lshl_add_u64 v[238:239], s[26:27], 0, v[166:167]
	global_load_lds_dwordx4 v[238:239], off
	v_lshl_add_u64 v[240:241], s[26:27], 0, v[164:165]
	s_mov_b32 m0, s41
	s_nop 0
	global_load_lds_dwordx4 v[240:241], off
	s_waitcnt vmcnt(6)
	s_barrier
	v_mfma_f32_16x16x32_bf16 v[58:61], v[214:217], v[146:149], v[58:61]
	v_mfma_f32_16x16x32_bf16 v[50:53], v[222:225], v[146:149], v[50:53]
	v_mfma_f32_16x16x32_bf16 v[42:45], v[214:217], v[154:157], v[42:45]
	v_mfma_f32_16x16x32_bf16 v[34:37], v[222:225], v[154:157], v[34:37]
	v_mfma_f32_16x16x32_bf16 v[26:29], v[214:217], v[176:179], v[26:29]
	v_mfma_f32_16x16x32_bf16 v[18:21], v[222:225], v[176:179], v[18:21]
	v_mfma_f32_16x16x32_bf16 v[10:13], v[214:217], v[206:209], v[10:13]
	v_mfma_f32_16x16x32_bf16 v[2:5], v[222:225], v[206:209], v[2:5]
	v_mfma_f32_16x16x32_bf16 v[58:61], v[218:221], v[150:153], v[58:61]
	v_mfma_f32_16x16x32_bf16 v[50:53], v[226:229], v[150:153], v[50:53]
	v_mfma_f32_16x16x32_bf16 v[42:45], v[218:221], v[158:161], v[42:45]
	v_mfma_f32_16x16x32_bf16 v[34:37], v[226:229], v[158:161], v[34:37]
	v_mfma_f32_16x16x32_bf16 v[26:29], v[218:221], v[202:205], v[26:29]
	v_mfma_f32_16x16x32_bf16 v[18:21], v[226:229], v[202:205], v[18:21]
	v_mfma_f32_16x16x32_bf16 v[10:13], v[218:221], v[210:213], v[10:13]
	v_mfma_f32_16x16x32_bf16 v[2:5], v[226:229], v[210:213], v[2:5]
	s_barrier
	ds_read_b128 v[122:125], v193
	ds_read_b128 v[126:129], v194
	ds_read_b128 v[138:141], v195
	ds_read_b128 v[142:145], v196
	s_add_u32 s2, s2, s22
	s_addc_u32 s3, s3, s23
	s_mov_b32 m0, s42
	v_lshl_add_u64 v[214:215], s[2:3], 0, v[166:167]
	ds_read_b128 v[146:149], v183 offset:32768
	ds_read_b128 v[150:153], v183 offset:33792
	ds_read_b128 v[154:157], v183 offset:34816
	ds_read_b128 v[158:161], v183 offset:35840
	ds_read_b128 v[176:179], v183 offset:36864
	ds_read_b128 v[202:205], v183 offset:37888
	ds_read_b128 v[206:209], v183 offset:38912
	ds_read_b128 v[210:213], v183 offset:39936
	global_load_lds_dwordx4 v[214:215], off
	v_lshl_add_u64 v[214:215], s[2:3], 0, v[164:165]
	s_mov_b32 m0, s43
	s_nop 0
	global_load_lds_dwordx4 v[214:215], off
	s_waitcnt lgkmcnt(8)
	s_barrier
	s_waitcnt lgkmcnt(0)
	s_waitcnt lgkmcnt(0)
	v_mfma_f32_16x16x32_bf16 v[134:137], v[122:125], v[146:149], v[134:137]
	v_mfma_f32_16x16x32_bf16 v[118:121], v[138:141], v[146:149], v[118:121]
	v_mfma_f32_16x16x32_bf16 v[110:113], v[122:125], v[154:157], v[110:113]
	v_mfma_f32_16x16x32_bf16 v[102:105], v[138:141], v[154:157], v[102:105]
	v_mfma_f32_16x16x32_bf16 v[94:97], v[122:125], v[176:179], v[94:97]
	v_mfma_f32_16x16x32_bf16 v[86:89], v[138:141], v[176:179], v[86:89]
	v_mfma_f32_16x16x32_bf16 v[78:81], v[122:125], v[206:209], v[78:81]
	v_mfma_f32_16x16x32_bf16 v[70:73], v[138:141], v[206:209], v[70:73]
	v_mfma_f32_16x16x32_bf16 v[134:137], v[126:129], v[150:153], v[134:137]
	v_mfma_f32_16x16x32_bf16 v[118:121], v[142:145], v[150:153], v[118:121]
	v_mfma_f32_16x16x32_bf16 v[110:113], v[126:129], v[158:161], v[110:113]
	v_mfma_f32_16x16x32_bf16 v[102:105], v[142:145], v[158:161], v[102:105]
	v_mfma_f32_16x16x32_bf16 v[94:97], v[126:129], v[202:205], v[94:97]
	v_mfma_f32_16x16x32_bf16 v[86:89], v[142:145], v[202:205], v[86:89]
	v_mfma_f32_16x16x32_bf16 v[78:81], v[126:129], v[210:213], v[78:81]
	v_mfma_f32_16x16x32_bf16 v[70:73], v[142:145], v[210:213], v[70:73]
	s_barrier
	s_mov_b32 m0, s48
	v_lshl_add_u64 v[230:231], v[230:231], 0, s[44:45]
	ds_read_b128 v[214:217], v197
	ds_read_b128 v[218:221], v198
	ds_read_b128 v[222:225], v199
	ds_read_b128 v[226:229], v200
	global_load_lds_dwordx4 v[230:231], off
	v_lshl_add_u64 v[230:231], v[232:233], 0, s[44:45]
	s_mov_b32 m0, s49
	s_nop 0
	global_load_lds_dwordx4 v[230:231], off
	s_barrier
	s_waitcnt lgkmcnt(0)
	s_waitcnt lgkmcnt(0)
	v_mfma_f32_16x16x32_bf16 v[130:133], v[214:217], v[146:149], v[130:133]
	v_mfma_f32_16x16x32_bf16 v[114:117], v[222:225], v[146:149], v[114:117]
	v_mfma_f32_16x16x32_bf16 v[106:109], v[214:217], v[154:157], v[106:109]
	v_mfma_f32_16x16x32_bf16 v[98:101], v[222:225], v[154:157], v[98:101]
	v_mfma_f32_16x16x32_bf16 v[90:93], v[214:217], v[176:179], v[90:93]
	v_mfma_f32_16x16x32_bf16 v[82:85], v[222:225], v[176:179], v[82:85]
	v_mfma_f32_16x16x32_bf16 v[74:77], v[214:217], v[206:209], v[74:77]
	v_mfma_f32_16x16x32_bf16 v[66:69], v[222:225], v[206:209], v[66:69]
	v_mfma_f32_16x16x32_bf16 v[130:133], v[218:221], v[150:153], v[130:133]
	v_mfma_f32_16x16x32_bf16 v[114:117], v[226:229], v[150:153], v[114:117]
	v_mfma_f32_16x16x32_bf16 v[106:109], v[218:221], v[158:161], v[106:109]
	v_mfma_f32_16x16x32_bf16 v[98:101], v[226:229], v[158:161], v[98:101]
	v_mfma_f32_16x16x32_bf16 v[90:93], v[218:221], v[202:205], v[90:93]
	v_mfma_f32_16x16x32_bf16 v[82:85], v[226:229], v[202:205], v[82:85]
	v_mfma_f32_16x16x32_bf16 v[74:77], v[218:221], v[210:213], v[74:77]
	v_mfma_f32_16x16x32_bf16 v[66:69], v[226:229], v[210:213], v[66:69]
	s_mov_b32 m0, s50
	v_lshl_add_u64 v[230:231], v[234:235], 0, s[44:45]
	s_barrier
	ds_read_b128 v[146:149], v183 offset:49152
	ds_read_b128 v[150:153], v183 offset:50176
	ds_read_b128 v[154:157], v183 offset:51200
	ds_read_b128 v[158:161], v183 offset:52224
	ds_read_b128 v[176:179], v183 offset:53248
	ds_read_b128 v[202:205], v183 offset:54272
	ds_read_b128 v[206:209], v183 offset:55296
	ds_read_b128 v[210:213], v183 offset:56320
	global_load_lds_dwordx4 v[230:231], off
	v_lshl_add_u64 v[230:231], v[236:237], 0, s[44:45]
	s_mov_b32 m0, s51
	s_nop 0
	global_load_lds_dwordx4 v[230:231], off
	s_barrier
	s_waitcnt lgkmcnt(0)
	s_waitcnt lgkmcnt(0)
	v_mfma_f32_16x16x32_bf16 v[62:65], v[122:125], v[146:149], v[62:65]
	v_mfma_f32_16x16x32_bf16 v[54:57], v[138:141], v[146:149], v[54:57]
	v_mfma_f32_16x16x32_bf16 v[46:49], v[122:125], v[154:157], v[46:49]
	v_mfma_f32_16x16x32_bf16 v[38:41], v[138:141], v[154:157], v[38:41]
	v_mfma_f32_16x16x32_bf16 v[30:33], v[122:125], v[176:179], v[30:33]
	v_mfma_f32_16x16x32_bf16 v[22:25], v[138:141], v[176:179], v[22:25]
	v_mfma_f32_16x16x32_bf16 v[14:17], v[122:125], v[206:209], v[14:17]
	v_mfma_f32_16x16x32_bf16 v[6:9], v[138:141], v[206:209], v[6:9]
	v_mfma_f32_16x16x32_bf16 v[62:65], v[126:129], v[150:153], v[62:65]
	v_mfma_f32_16x16x32_bf16 v[54:57], v[142:145], v[150:153], v[54:57]
	v_mfma_f32_16x16x32_bf16 v[46:49], v[126:129], v[158:161], v[46:49]
	v_mfma_f32_16x16x32_bf16 v[38:41], v[142:145], v[158:161], v[38:41]
	v_mfma_f32_16x16x32_bf16 v[30:33], v[126:129], v[202:205], v[30:33]
	v_mfma_f32_16x16x32_bf16 v[22:25], v[142:145], v[202:205], v[22:25]
	v_mfma_f32_16x16x32_bf16 v[14:17], v[126:129], v[210:213], v[14:17]
	v_mfma_f32_16x16x32_bf16 v[6:9], v[142:145], v[210:213], v[6:9]
	s_barrier
	s_mov_b32 m0, s53
	v_lshl_add_u64 v[122:123], v[238:239], 0, s[44:45]
	global_load_lds_dwordx4 v[122:123], off
	v_lshl_add_u64 v[122:123], v[240:241], 0, s[44:45]
	s_mov_b32 m0, s56
	s_nop 0
	global_load_lds_dwordx4 v[122:123], off
	s_waitcnt vmcnt(6)
	s_barrier
	v_mfma_f32_16x16x32_bf16 v[58:61], v[214:217], v[146:149], v[58:61]
	v_mfma_f32_16x16x32_bf16 v[50:53], v[222:225], v[146:149], v[50:53]
	v_mfma_f32_16x16x32_bf16 v[42:45], v[214:217], v[154:157], v[42:45]
	v_mfma_f32_16x16x32_bf16 v[34:37], v[222:225], v[154:157], v[34:37]
	v_mfma_f32_16x16x32_bf16 v[26:29], v[214:217], v[176:179], v[26:29]
	v_mfma_f32_16x16x32_bf16 v[18:21], v[222:225], v[176:179], v[18:21]
	v_mfma_f32_16x16x32_bf16 v[10:13], v[214:217], v[206:209], v[10:13]
	v_mfma_f32_16x16x32_bf16 v[2:5], v[222:225], v[206:209], v[2:5]
	v_mfma_f32_16x16x32_bf16 v[58:61], v[218:221], v[150:153], v[58:61]
	v_mfma_f32_16x16x32_bf16 v[50:53], v[226:229], v[150:153], v[50:53]
	v_mfma_f32_16x16x32_bf16 v[42:45], v[218:221], v[158:161], v[42:45]
	v_mfma_f32_16x16x32_bf16 v[34:37], v[226:229], v[158:161], v[34:37]
	v_mfma_f32_16x16x32_bf16 v[26:29], v[218:221], v[202:205], v[26:29]
	v_mfma_f32_16x16x32_bf16 v[18:21], v[226:229], v[202:205], v[18:21]
	v_mfma_f32_16x16x32_bf16 v[10:13], v[218:221], v[210:213], v[10:13]
	v_mfma_f32_16x16x32_bf16 v[2:5], v[226:229], v[210:213], v[2:5]
	s_add_u32 s0, s0, 0x100
	s_addc_u32 s1, s1, 0
	s_add_u32 s28, s28, 0x100
	s_addc_u32 s29, s29, 0
	s_cmp_ge_i32 s36, s57
	s_mov_b32 s2, s36
	s_barrier
	s_cbranch_scc0 .LBB0_1104
	s_branch .LBB0_1095

.LBB0_1149:
	ds_read_b128 v[142:145], v176
	ds_read_b128 v[146:149], v177
	ds_read_b128 v[150:153], v178
	ds_read_b128 v[154:157], v179
	s_add_i32 s36, s2, 2
	s_add_u32 s26, s54, 0x80
	s_addc_u32 s3, s55, 0
	s_cmp_eq_u32 s51, s2
	s_cselect_b32 s2, s10, s26
	s_cselect_b32 s3, s11, s3
	s_cselect_b32 s27, s1, s29
	s_cselect_b32 s26, s0, s28
	s_mov_b32 m0, s59
	v_lshl_add_u64 v[168:169], s[54:55], 0, v[134:135]
	ds_read_b128 v[158:161], v174
	ds_read_b128 v[164:167], v174 offset:1024
	ds_read_b128 v[194:197], v174 offset:2048
	ds_read_b128 v[198:201], v174 offset:3072
	ds_read_b128 v[202:205], v174 offset:4096
	ds_read_b128 v[206:209], v174 offset:5120
	ds_read_b128 v[210:213], v174 offset:6144
	ds_read_b128 v[214:217], v174 offset:7168
	global_load_lds_dwordx4 v[168:169], off
	v_lshl_add_u64 v[168:169], s[54:55], 0, v[136:137]
	s_mov_b32 m0, s60
	s_nop 0
	global_load_lds_dwordx4 v[168:169], off
	s_waitcnt lgkmcnt(8)
	s_barrier
	s_waitcnt lgkmcnt(0)
	s_waitcnt lgkmcnt(0)
	v_mfma_f32_16x16x32_bf16 v[126:129], v[142:145], v[158:161], v[126:129]
	v_mfma_f32_16x16x32_bf16 v[122:125], v[150:153], v[158:161], v[122:125]
	v_mfma_f32_16x16x32_bf16 v[110:113], v[142:145], v[194:197], v[110:113]
	v_mfma_f32_16x16x32_bf16 v[106:109], v[150:153], v[194:197], v[106:109]
	v_mfma_f32_16x16x32_bf16 v[94:97], v[142:145], v[202:205], v[94:97]
	v_mfma_f32_16x16x32_bf16 v[90:93], v[150:153], v[202:205], v[90:93]
	v_mfma_f32_16x16x32_bf16 v[78:81], v[142:145], v[210:213], v[78:81]
	v_mfma_f32_16x16x32_bf16 v[74:77], v[150:153], v[210:213], v[74:77]
	v_mfma_f32_16x16x32_bf16 v[126:129], v[146:149], v[164:167], v[126:129]
	v_mfma_f32_16x16x32_bf16 v[122:125], v[154:157], v[164:167], v[122:125]
	v_mfma_f32_16x16x32_bf16 v[110:113], v[146:149], v[198:201], v[110:113]
	v_mfma_f32_16x16x32_bf16 v[106:109], v[154:157], v[198:201], v[106:109]
	v_mfma_f32_16x16x32_bf16 v[94:97], v[146:149], v[206:209], v[94:97]
	v_mfma_f32_16x16x32_bf16 v[90:93], v[154:157], v[206:209], v[90:93]
	v_mfma_f32_16x16x32_bf16 v[78:81], v[146:149], v[214:217], v[78:81]
	v_mfma_f32_16x16x32_bf16 v[74:77], v[154:157], v[214:217], v[74:77]
	s_barrier
	s_mov_b32 m0, s33
	v_lshl_add_u64 v[168:169], s[26:27], 0, v[130:131]
	ds_read_b128 v[218:221], v180
	ds_read_b128 v[222:225], v181
	ds_read_b128 v[226:229], v182
	ds_read_b128 v[230:233], v183
	global_load_lds_dwordx4 v[168:169], off
	v_lshl_add_u64 v[234:235], s[26:27], 0, v[132:133]
	s_mov_b32 m0, s34
	s_nop 0
	global_load_lds_dwordx4 v[234:235], off
	s_barrier
	s_waitcnt lgkmcnt(0)
	s_waitcnt lgkmcnt(0)
	v_mfma_f32_16x16x32_bf16 v[118:121], v[218:221], v[158:161], v[118:121]
	v_mfma_f32_16x16x32_bf16 v[114:117], v[226:229], v[158:161], v[114:117]
	v_mfma_f32_16x16x32_bf16 v[102:105], v[218:221], v[194:197], v[102:105]
	v_mfma_f32_16x16x32_bf16 v[98:101], v[226:229], v[194:197], v[98:101]
	v_mfma_f32_16x16x32_bf16 v[86:89], v[218:221], v[202:205], v[86:89]
	v_mfma_f32_16x16x32_bf16 v[82:85], v[226:229], v[202:205], v[82:85]
	v_mfma_f32_16x16x32_bf16 v[70:73], v[218:221], v[210:213], v[70:73]
	v_mfma_f32_16x16x32_bf16 v[66:69], v[226:229], v[210:213], v[66:69]
	v_mfma_f32_16x16x32_bf16 v[118:121], v[222:225], v[164:167], v[118:121]
	v_mfma_f32_16x16x32_bf16 v[114:117], v[230:233], v[164:167], v[114:117]
	v_mfma_f32_16x16x32_bf16 v[102:105], v[222:225], v[198:201], v[102:105]
	v_mfma_f32_16x16x32_bf16 v[98:101], v[230:233], v[198:201], v[98:101]
	v_mfma_f32_16x16x32_bf16 v[86:89], v[222:225], v[206:209], v[86:89]
	v_mfma_f32_16x16x32_bf16 v[82:85], v[230:233], v[206:209], v[82:85]
	v_mfma_f32_16x16x32_bf16 v[70:73], v[222:225], v[214:217], v[70:73]
	v_mfma_f32_16x16x32_bf16 v[66:69], v[230:233], v[214:217], v[66:69]
	s_mov_b32 m0, s31
	v_lshl_add_u64 v[236:237], s[2:3], 0, v[130:131]
	s_barrier
	ds_read_b128 v[158:161], v174 offset:16384
	ds_read_b128 v[164:167], v174 offset:17408
	ds_read_b128 v[194:197], v174 offset:18432
	ds_read_b128 v[198:201], v174 offset:19456
	ds_read_b128 v[202:205], v174 offset:20480
	ds_read_b128 v[206:209], v174 offset:21504
	ds_read_b128 v[210:213], v174 offset:22528
	ds_read_b128 v[214:217], v174 offset:23552
	global_load_lds_dwordx4 v[236:237], off
	v_lshl_add_u64 v[238:239], s[2:3], 0, v[132:133]
	s_mov_b32 m0, s35
	s_nop 0
	global_load_lds_dwordx4 v[238:239], off
	s_barrier
	s_waitcnt lgkmcnt(0)
	s_waitcnt lgkmcnt(0)
	v_mfma_f32_16x16x32_bf16 v[62:65], v[142:145], v[158:161], v[62:65]
	v_mfma_f32_16x16x32_bf16 v[58:61], v[150:153], v[158:161], v[58:61]
	v_mfma_f32_16x16x32_bf16 v[46:49], v[142:145], v[194:197], v[46:49]
	v_mfma_f32_16x16x32_bf16 v[42:45], v[150:153], v[194:197], v[42:45]
	v_mfma_f32_16x16x32_bf16 v[30:33], v[142:145], v[202:205], v[30:33]
	v_mfma_f32_16x16x32_bf16 v[26:29], v[150:153], v[202:205], v[26:29]
	v_mfma_f32_16x16x32_bf16 v[14:17], v[142:145], v[210:213], v[14:17]
	v_mfma_f32_16x16x32_bf16 v[10:13], v[150:153], v[210:213], v[10:13]
	v_mfma_f32_16x16x32_bf16 v[62:65], v[146:149], v[164:167], v[62:65]
	v_mfma_f32_16x16x32_bf16 v[58:61], v[154:157], v[164:167], v[58:61]
	v_mfma_f32_16x16x32_bf16 v[46:49], v[146:149], v[198:201], v[46:49]
	v_mfma_f32_16x16x32_bf16 v[42:45], v[154:157], v[198:201], v[42:45]
	v_mfma_f32_16x16x32_bf16 v[30:33], v[146:149], v[206:209], v[30:33]
	v_mfma_f32_16x16x32_bf16 v[26:29], v[154:157], v[206:209], v[26:29]
	v_mfma_f32_16x16x32_bf16 v[14:17], v[146:149], v[214:217], v[14:17]
	v_mfma_f32_16x16x32_bf16 v[10:13], v[154:157], v[214:217], v[10:13]
	s_barrier
	s_add_u32 s26, s26, s20
	s_addc_u32 s27, s27, s21
	s_mov_b32 m0, s38
	v_lshl_add_u64 v[240:241], s[26:27], 0, v[130:131]
	global_load_lds_dwordx4 v[240:241], off
	v_lshl_add_u64 v[242:243], s[26:27], 0, v[132:133]
	s_mov_b32 m0, s39
	s_nop 0
	global_load_lds_dwordx4 v[242:243], off
	s_waitcnt vmcnt(6)
	s_barrier
	v_mfma_f32_16x16x32_bf16 v[54:57], v[218:221], v[158:161], v[54:57]
	v_mfma_f32_16x16x32_bf16 v[50:53], v[226:229], v[158:161], v[50:53]
	v_mfma_f32_16x16x32_bf16 v[38:41], v[218:221], v[194:197], v[38:41]
	v_mfma_f32_16x16x32_bf16 v[34:37], v[226:229], v[194:197], v[34:37]
	v_mfma_f32_16x16x32_bf16 v[22:25], v[218:221], v[202:205], v[22:25]
	v_mfma_f32_16x16x32_bf16 v[18:21], v[226:229], v[202:205], v[18:21]
	v_mfma_f32_16x16x32_bf16 v[6:9], v[218:221], v[210:213], v[6:9]
	v_mfma_f32_16x16x32_bf16 v[2:5], v[226:229], v[210:213], v[2:5]
	v_mfma_f32_16x16x32_bf16 v[54:57], v[222:225], v[164:167], v[54:57]
	v_mfma_f32_16x16x32_bf16 v[50:53], v[230:233], v[164:167], v[50:53]
	v_mfma_f32_16x16x32_bf16 v[38:41], v[222:225], v[198:201], v[38:41]
	v_mfma_f32_16x16x32_bf16 v[34:37], v[230:233], v[198:201], v[34:37]
	v_mfma_f32_16x16x32_bf16 v[22:25], v[222:225], v[206:209], v[22:25]
	v_mfma_f32_16x16x32_bf16 v[18:21], v[230:233], v[206:209], v[18:21]
	v_mfma_f32_16x16x32_bf16 v[6:9], v[222:225], v[214:217], v[6:9]
	v_mfma_f32_16x16x32_bf16 v[2:5], v[230:233], v[214:217], v[2:5]
	s_barrier
	ds_read_b128 v[142:145], v184
	ds_read_b128 v[146:149], v185
	ds_read_b128 v[150:153], v186
	ds_read_b128 v[154:157], v187
	s_add_u32 s2, s2, s20
	s_addc_u32 s3, s3, s21
	s_mov_b32 m0, s40
	v_lshl_add_u64 v[218:219], s[2:3], 0, v[130:131]
	ds_read_b128 v[158:161], v174 offset:32768
	ds_read_b128 v[164:167], v174 offset:33792
	ds_read_b128 v[194:197], v174 offset:34816
	ds_read_b128 v[198:201], v174 offset:35840
	ds_read_b128 v[202:205], v174 offset:36864
	ds_read_b128 v[206:209], v174 offset:37888
	ds_read_b128 v[210:213], v174 offset:38912
	ds_read_b128 v[214:217], v174 offset:39936
	global_load_lds_dwordx4 v[218:219], off
	v_lshl_add_u64 v[218:219], s[2:3], 0, v[132:133]
	s_mov_b32 m0, s41
	s_nop 0
	global_load_lds_dwordx4 v[218:219], off
	s_waitcnt lgkmcnt(8)
	s_barrier
	s_waitcnt lgkmcnt(0)
	s_waitcnt lgkmcnt(0)
	v_mfma_f32_16x16x32_bf16 v[126:129], v[142:145], v[158:161], v[126:129]
	v_mfma_f32_16x16x32_bf16 v[122:125], v[150:153], v[158:161], v[122:125]
	v_mfma_f32_16x16x32_bf16 v[110:113], v[142:145], v[194:197], v[110:113]
	v_mfma_f32_16x16x32_bf16 v[106:109], v[150:153], v[194:197], v[106:109]
	v_mfma_f32_16x16x32_bf16 v[94:97], v[142:145], v[202:205], v[94:97]
	v_mfma_f32_16x16x32_bf16 v[90:93], v[150:153], v[202:205], v[90:93]
	v_mfma_f32_16x16x32_bf16 v[78:81], v[142:145], v[210:213], v[78:81]
	v_mfma_f32_16x16x32_bf16 v[74:77], v[150:153], v[210:213], v[74:77]
	v_mfma_f32_16x16x32_bf16 v[126:129], v[146:149], v[164:167], v[126:129]
	v_mfma_f32_16x16x32_bf16 v[122:125], v[154:157], v[164:167], v[122:125]
	v_mfma_f32_16x16x32_bf16 v[110:113], v[146:149], v[198:201], v[110:113]
	v_mfma_f32_16x16x32_bf16 v[106:109], v[154:157], v[198:201], v[106:109]
	v_mfma_f32_16x16x32_bf16 v[94:97], v[146:149], v[206:209], v[94:97]
	v_mfma_f32_16x16x32_bf16 v[90:93], v[154:157], v[206:209], v[90:93]
	v_mfma_f32_16x16x32_bf16 v[78:81], v[146:149], v[214:217], v[78:81]
	v_mfma_f32_16x16x32_bf16 v[74:77], v[154:157], v[214:217], v[74:77]
	s_barrier
	s_mov_b32 m0, s42
	v_lshl_add_u64 v[168:169], v[168:169], 0, s[24:25]
	ds_read_b128 v[218:221], v188
	ds_read_b128 v[222:225], v189
	ds_read_b128 v[226:229], v190
	ds_read_b128 v[230:233], v191
	global_load_lds_dwordx4 v[168:169], off
	v_lshl_add_u64 v[168:169], v[234:235], 0, s[24:25]
	s_mov_b32 m0, s43
	s_nop 0
	global_load_lds_dwordx4 v[168:169], off
	s_barrier
	s_waitcnt lgkmcnt(0)
	s_waitcnt lgkmcnt(0)
	v_mfma_f32_16x16x32_bf16 v[118:121], v[218:221], v[158:161], v[118:121]
	v_mfma_f32_16x16x32_bf16 v[114:117], v[226:229], v[158:161], v[114:117]
	v_mfma_f32_16x16x32_bf16 v[102:105], v[218:221], v[194:197], v[102:105]
	v_mfma_f32_16x16x32_bf16 v[98:101], v[226:229], v[194:197], v[98:101]
	v_mfma_f32_16x16x32_bf16 v[86:89], v[218:221], v[202:205], v[86:89]
	v_mfma_f32_16x16x32_bf16 v[82:85], v[226:229], v[202:205], v[82:85]
	v_mfma_f32_16x16x32_bf16 v[70:73], v[218:221], v[210:213], v[70:73]
	v_mfma_f32_16x16x32_bf16 v[66:69], v[226:229], v[210:213], v[66:69]
	v_mfma_f32_16x16x32_bf16 v[118:121], v[222:225], v[164:167], v[118:121]
	v_mfma_f32_16x16x32_bf16 v[114:117], v[230:233], v[164:167], v[114:117]
	v_mfma_f32_16x16x32_bf16 v[102:105], v[222:225], v[198:201], v[102:105]
	v_mfma_f32_16x16x32_bf16 v[98:101], v[230:233], v[198:201], v[98:101]
	v_mfma_f32_16x16x32_bf16 v[86:89], v[222:225], v[206:209], v[86:89]
	v_mfma_f32_16x16x32_bf16 v[82:85], v[230:233], v[206:209], v[82:85]
	v_mfma_f32_16x16x32_bf16 v[70:73], v[222:225], v[214:217], v[70:73]
	v_mfma_f32_16x16x32_bf16 v[66:69], v[230:233], v[214:217], v[66:69]
	s_mov_b32 m0, s45
	v_lshl_add_u64 v[168:169], v[236:237], 0, s[24:25]
	s_barrier
	ds_read_b128 v[158:161], v174 offset:49152
	ds_read_b128 v[164:167], v174 offset:50176
	ds_read_b128 v[194:197], v174 offset:51200
	ds_read_b128 v[198:201], v174 offset:52224
	ds_read_b128 v[202:205], v174 offset:53248
	ds_read_b128 v[206:209], v174 offset:54272
	ds_read_b128 v[210:213], v174 offset:55296
	ds_read_b128 v[214:217], v174 offset:56320
	global_load_lds_dwordx4 v[168:169], off
	v_lshl_add_u64 v[168:169], v[238:239], 0, s[24:25]
	s_mov_b32 m0, s47
	s_nop 0
	global_load_lds_dwordx4 v[168:169], off
	s_barrier
	s_waitcnt lgkmcnt(0)
	s_waitcnt lgkmcnt(0)
	v_mfma_f32_16x16x32_bf16 v[62:65], v[142:145], v[158:161], v[62:65]
	v_mfma_f32_16x16x32_bf16 v[58:61], v[150:153], v[158:161], v[58:61]
	v_mfma_f32_16x16x32_bf16 v[46:49], v[142:145], v[194:197], v[46:49]
	v_mfma_f32_16x16x32_bf16 v[42:45], v[150:153], v[194:197], v[42:45]
	v_mfma_f32_16x16x32_bf16 v[30:33], v[142:145], v[202:205], v[30:33]
	v_mfma_f32_16x16x32_bf16 v[26:29], v[150:153], v[202:205], v[26:29]
	v_mfma_f32_16x16x32_bf16 v[14:17], v[142:145], v[210:213], v[14:17]
	v_mfma_f32_16x16x32_bf16 v[10:13], v[150:153], v[210:213], v[10:13]
	v_mfma_f32_16x16x32_bf16 v[62:65], v[146:149], v[164:167], v[62:65]
	v_mfma_f32_16x16x32_bf16 v[58:61], v[154:157], v[164:167], v[58:61]
	v_mfma_f32_16x16x32_bf16 v[46:49], v[146:149], v[198:201], v[46:49]
	v_mfma_f32_16x16x32_bf16 v[42:45], v[154:157], v[198:201], v[42:45]
	v_mfma_f32_16x16x32_bf16 v[30:33], v[146:149], v[206:209], v[30:33]
	v_mfma_f32_16x16x32_bf16 v[26:29], v[154:157], v[206:209], v[26:29]
	v_mfma_f32_16x16x32_bf16 v[14:17], v[146:149], v[214:217], v[14:17]
	v_mfma_f32_16x16x32_bf16 v[10:13], v[154:157], v[214:217], v[10:13]
	s_barrier
	s_mov_b32 m0, s48
	v_lshl_add_u64 v[142:143], v[240:241], 0, s[24:25]
	global_load_lds_dwordx4 v[142:143], off
	v_lshl_add_u64 v[142:143], v[242:243], 0, s[24:25]
	s_mov_b32 m0, s49
	s_nop 0
	global_load_lds_dwordx4 v[142:143], off
	s_waitcnt vmcnt(6)
	s_barrier
	v_mfma_f32_16x16x32_bf16 v[54:57], v[218:221], v[158:161], v[54:57]
	v_mfma_f32_16x16x32_bf16 v[50:53], v[226:229], v[158:161], v[50:53]
	v_mfma_f32_16x16x32_bf16 v[38:41], v[218:221], v[194:197], v[38:41]
	v_mfma_f32_16x16x32_bf16 v[34:37], v[226:229], v[194:197], v[34:37]
	v_mfma_f32_16x16x32_bf16 v[22:25], v[218:221], v[202:205], v[22:25]
	v_mfma_f32_16x16x32_bf16 v[18:21], v[226:229], v[202:205], v[18:21]
	v_mfma_f32_16x16x32_bf16 v[6:9], v[218:221], v[210:213], v[6:9]
	v_mfma_f32_16x16x32_bf16 v[2:5], v[226:229], v[210:213], v[2:5]
	v_mfma_f32_16x16x32_bf16 v[54:57], v[222:225], v[164:167], v[54:57]
	v_mfma_f32_16x16x32_bf16 v[50:53], v[230:233], v[164:167], v[50:53]
	v_mfma_f32_16x16x32_bf16 v[38:41], v[222:225], v[198:201], v[38:41]
	v_mfma_f32_16x16x32_bf16 v[34:37], v[230:233], v[198:201], v[34:37]
	v_mfma_f32_16x16x32_bf16 v[22:25], v[222:225], v[206:209], v[22:25]
	v_mfma_f32_16x16x32_bf16 v[18:21], v[230:233], v[206:209], v[18:21]
	v_mfma_f32_16x16x32_bf16 v[6:9], v[222:225], v[214:217], v[6:9]
	v_mfma_f32_16x16x32_bf16 v[2:5], v[230:233], v[214:217], v[2:5]
	s_add_u32 s54, s54, 0x100
	s_addc_u32 s55, s55, 0
	s_add_u32 s28, s28, 0x100
	s_addc_u32 s29, s29, 0
	s_cmp_ge_i32 s36, s50
	s_mov_b32 s2, s36
	s_barrier
	s_cbranch_scc0 .LBB0_1149

.LBB0_1255:
	ds_read_b128 v[146:149], v177
	ds_read_b128 v[150:153], v178
	ds_read_b128 v[154:157], v179
	ds_read_b128 v[158:161], v180
	s_add_i32 s72, s2, 2
	s_add_u32 s28, s26, 0x80
	s_addc_u32 s3, s27, 0
	s_cmp_eq_u32 s64, s2
	s_cselect_b32 s2, s54, s28
	s_cselect_b32 s3, s55, s3
	s_cselect_b32 s29, s1, s53
	s_cselect_b32 s28, s0, s37
	s_mov_b32 m0, s66
	v_lshl_add_u64 v[68:69], s[26:27], 0, v[138:139]
	ds_read_b128 v[164:167], v174
	ds_read_b128 v[168:171], v174 offset:1024
	ds_read_b128 v[194:197], v174 offset:2048
	ds_read_b128 v[198:201], v174 offset:3072
	ds_read_b128 v[206:209], v174 offset:4096
	ds_read_b128 v[210:213], v174 offset:5120
	ds_read_b128 v[214:217], v174 offset:6144
	ds_read_b128 v[218:221], v174 offset:7168
	global_load_lds_dwordx4 v[68:69], off
	v_lshl_add_u64 v[68:69], s[26:27], 0, v[140:141]
	s_mov_b32 m0, s67
	s_nop 0
	global_load_lds_dwordx4 v[68:69], off
	s_waitcnt lgkmcnt(8)
	s_barrier
	s_waitcnt lgkmcnt(0)
	s_waitcnt lgkmcnt(0)
	v_mfma_f32_16x16x32_bf16 v[130:133], v[146:149], v[164:167], v[130:133]
	v_mfma_f32_16x16x32_bf16 v[126:129], v[154:157], v[164:167], v[126:129]
	v_mfma_f32_16x16x32_bf16 v[114:117], v[146:149], v[194:197], v[114:117]
	v_mfma_f32_16x16x32_bf16 v[110:113], v[154:157], v[194:197], v[110:113]
	v_mfma_f32_16x16x32_bf16 v[98:101], v[146:149], v[206:209], v[98:101]
	v_mfma_f32_16x16x32_bf16 v[94:97], v[154:157], v[206:209], v[94:97]
	v_mfma_f32_16x16x32_bf16 v[82:85], v[146:149], v[214:217], v[82:85]
	v_mfma_f32_16x16x32_bf16 v[78:81], v[154:157], v[214:217], v[78:81]
	v_mfma_f32_16x16x32_bf16 v[130:133], v[150:153], v[168:171], v[130:133]
	v_mfma_f32_16x16x32_bf16 v[126:129], v[158:161], v[168:171], v[126:129]
	v_mfma_f32_16x16x32_bf16 v[114:117], v[150:153], v[198:201], v[114:117]
	v_mfma_f32_16x16x32_bf16 v[110:113], v[158:161], v[198:201], v[110:113]
	v_mfma_f32_16x16x32_bf16 v[98:101], v[150:153], v[210:213], v[98:101]
	v_mfma_f32_16x16x32_bf16 v[94:97], v[158:161], v[210:213], v[94:97]
	v_mfma_f32_16x16x32_bf16 v[82:85], v[150:153], v[218:221], v[82:85]
	v_mfma_f32_16x16x32_bf16 v[78:81], v[158:161], v[218:221], v[78:81]
	s_barrier
	s_mov_b32 m0, s38
	v_lshl_add_u64 v[238:239], s[28:29], 0, v[134:135]
	ds_read_b128 v[222:225], v181
	ds_read_b128 v[226:229], v182
	ds_read_b128 v[230:233], v183
	ds_read_b128 v[234:237], v184
	global_load_lds_dwordx4 v[238:239], off
	v_lshl_add_u64 v[240:241], s[28:29], 0, v[136:137]
	s_mov_b32 m0, s39
	s_nop 0
	global_load_lds_dwordx4 v[240:241], off
	s_barrier
	s_waitcnt lgkmcnt(0)
	s_waitcnt lgkmcnt(0)
	v_mfma_f32_16x16x32_bf16 v[122:125], v[222:225], v[164:167], v[122:125]
	v_mfma_f32_16x16x32_bf16 v[118:121], v[230:233], v[164:167], v[118:121]
	v_mfma_f32_16x16x32_bf16 v[106:109], v[222:225], v[194:197], v[106:109]
	v_mfma_f32_16x16x32_bf16 v[102:105], v[230:233], v[194:197], v[102:105]
	v_mfma_f32_16x16x32_bf16 v[90:93], v[222:225], v[206:209], v[90:93]
	v_mfma_f32_16x16x32_bf16 v[86:89], v[230:233], v[206:209], v[86:89]
	v_mfma_f32_16x16x32_bf16 v[74:77], v[222:225], v[214:217], v[74:77]
	v_mfma_f32_16x16x32_bf16 v[68:71], v[230:233], v[214:217], v[70:73]
	v_mfma_f32_16x16x32_bf16 v[122:125], v[226:229], v[168:171], v[122:125]
	v_mfma_f32_16x16x32_bf16 v[118:121], v[234:237], v[168:171], v[118:121]
	v_mfma_f32_16x16x32_bf16 v[106:109], v[226:229], v[198:201], v[106:109]
	v_mfma_f32_16x16x32_bf16 v[102:105], v[234:237], v[198:201], v[102:105]
	v_mfma_f32_16x16x32_bf16 v[90:93], v[226:229], v[210:213], v[90:93]
	v_mfma_f32_16x16x32_bf16 v[86:89], v[234:237], v[210:213], v[86:89]
	v_mfma_f32_16x16x32_bf16 v[74:77], v[226:229], v[218:221], v[74:77]
	v_mfma_f32_16x16x32_bf16 v[68:71], v[234:237], v[218:221], v[68:71]
	s_mov_b32 m0, s35
	v_lshl_add_u64 v[242:243], s[2:3], 0, v[134:135]
	s_barrier
	ds_read_b128 v[164:167], v174 offset:16384
	ds_read_b128 v[168:171], v174 offset:17408
	ds_read_b128 v[194:197], v174 offset:18432
	ds_read_b128 v[198:201], v174 offset:19456
	ds_read_b128 v[206:209], v174 offset:20480
	ds_read_b128 v[210:213], v174 offset:21504
	ds_read_b128 v[214:217], v174 offset:22528
	ds_read_b128 v[218:221], v174 offset:23552
	global_load_lds_dwordx4 v[242:243], off
	v_lshl_add_u64 v[244:245], s[2:3], 0, v[136:137]
	s_mov_b32 m0, s40
	s_nop 0
	global_load_lds_dwordx4 v[244:245], off
	s_barrier
	s_waitcnt lgkmcnt(0)
	s_waitcnt lgkmcnt(0)
	v_mfma_f32_16x16x32_bf16 v[62:65], v[146:149], v[164:167], v[62:65]
	v_mfma_f32_16x16x32_bf16 v[58:61], v[154:157], v[164:167], v[58:61]
	v_mfma_f32_16x16x32_bf16 v[46:49], v[146:149], v[194:197], v[46:49]
	v_mfma_f32_16x16x32_bf16 v[42:45], v[154:157], v[194:197], v[42:45]
	v_mfma_f32_16x16x32_bf16 v[30:33], v[146:149], v[206:209], v[30:33]
	v_mfma_f32_16x16x32_bf16 v[26:29], v[154:157], v[206:209], v[26:29]
	v_mfma_f32_16x16x32_bf16 v[14:17], v[146:149], v[214:217], v[14:17]
	v_mfma_f32_16x16x32_bf16 v[10:13], v[154:157], v[214:217], v[10:13]
	v_mfma_f32_16x16x32_bf16 v[62:65], v[150:153], v[168:171], v[62:65]
	v_mfma_f32_16x16x32_bf16 v[58:61], v[158:161], v[168:171], v[58:61]
	v_mfma_f32_16x16x32_bf16 v[46:49], v[150:153], v[198:201], v[46:49]
	v_mfma_f32_16x16x32_bf16 v[42:45], v[158:161], v[198:201], v[42:45]
	v_mfma_f32_16x16x32_bf16 v[30:33], v[150:153], v[210:213], v[30:33]
	v_mfma_f32_16x16x32_bf16 v[26:29], v[158:161], v[210:213], v[26:29]
	v_mfma_f32_16x16x32_bf16 v[14:17], v[150:153], v[218:221], v[14:17]
	v_mfma_f32_16x16x32_bf16 v[10:13], v[158:161], v[218:221], v[10:13]
	s_barrier
	s_add_u32 s28, s28, s20
	s_addc_u32 s29, s29, s21
	s_mov_b32 m0, s41
	v_lshl_add_u64 v[246:247], s[28:29], 0, v[134:135]
	global_load_lds_dwordx4 v[246:247], off
	v_lshl_add_u64 v[248:249], s[28:29], 0, v[136:137]
	s_mov_b32 m0, s42
	s_nop 0
	global_load_lds_dwordx4 v[248:249], off
	s_waitcnt vmcnt(6)
	s_barrier
	v_mfma_f32_16x16x32_bf16 v[54:57], v[222:225], v[164:167], v[54:57]
	v_mfma_f32_16x16x32_bf16 v[50:53], v[230:233], v[164:167], v[50:53]
	v_mfma_f32_16x16x32_bf16 v[38:41], v[222:225], v[194:197], v[38:41]
	v_mfma_f32_16x16x32_bf16 v[34:37], v[230:233], v[194:197], v[34:37]
	v_mfma_f32_16x16x32_bf16 v[22:25], v[222:225], v[206:209], v[22:25]
	v_mfma_f32_16x16x32_bf16 v[18:21], v[230:233], v[206:209], v[18:21]
	v_mfma_f32_16x16x32_bf16 v[6:9], v[222:225], v[214:217], v[6:9]
	v_mfma_f32_16x16x32_bf16 v[2:5], v[230:233], v[214:217], v[2:5]
	v_mfma_f32_16x16x32_bf16 v[54:57], v[226:229], v[168:171], v[54:57]
	v_mfma_f32_16x16x32_bf16 v[50:53], v[234:237], v[168:171], v[50:53]
	v_mfma_f32_16x16x32_bf16 v[38:41], v[226:229], v[198:201], v[38:41]
	v_mfma_f32_16x16x32_bf16 v[34:37], v[234:237], v[198:201], v[34:37]
	v_mfma_f32_16x16x32_bf16 v[22:25], v[226:229], v[210:213], v[22:25]
	v_mfma_f32_16x16x32_bf16 v[18:21], v[234:237], v[210:213], v[18:21]
	v_mfma_f32_16x16x32_bf16 v[6:9], v[226:229], v[218:221], v[6:9]
	v_mfma_f32_16x16x32_bf16 v[2:5], v[234:237], v[218:221], v[2:5]
	s_barrier
	ds_read_b128 v[146:149], v185
	ds_read_b128 v[150:153], v186
	ds_read_b128 v[154:157], v187
	ds_read_b128 v[158:161], v188
	s_add_u32 s2, s2, s20
	s_addc_u32 s3, s3, s21
	s_mov_b32 m0, s43
	v_lshl_add_u64 v[72:73], s[2:3], 0, v[134:135]
	ds_read_b128 v[164:167], v174 offset:32768
	ds_read_b128 v[168:171], v174 offset:33792
	ds_read_b128 v[194:197], v174 offset:34816
	ds_read_b128 v[198:201], v174 offset:35840
	ds_read_b128 v[206:209], v174 offset:36864
	ds_read_b128 v[210:213], v174 offset:37888
	ds_read_b128 v[214:217], v174 offset:38912
	ds_read_b128 v[218:221], v174 offset:39936
	global_load_lds_dwordx4 v[72:73], off
	v_lshl_add_u64 v[72:73], s[2:3], 0, v[136:137]
	s_mov_b32 m0, s45
	s_nop 0
	global_load_lds_dwordx4 v[72:73], off
	s_waitcnt lgkmcnt(8)
	s_barrier
	s_waitcnt lgkmcnt(0)
	s_waitcnt lgkmcnt(0)
	v_mfma_f32_16x16x32_bf16 v[130:133], v[146:149], v[164:167], v[130:133]
	v_mfma_f32_16x16x32_bf16 v[126:129], v[154:157], v[164:167], v[126:129]
	v_mfma_f32_16x16x32_bf16 v[114:117], v[146:149], v[194:197], v[114:117]
	v_mfma_f32_16x16x32_bf16 v[110:113], v[154:157], v[194:197], v[110:113]
	v_mfma_f32_16x16x32_bf16 v[98:101], v[146:149], v[206:209], v[98:101]
	v_mfma_f32_16x16x32_bf16 v[94:97], v[154:157], v[206:209], v[94:97]
	v_mfma_f32_16x16x32_bf16 v[82:85], v[146:149], v[214:217], v[82:85]
	v_mfma_f32_16x16x32_bf16 v[78:81], v[154:157], v[214:217], v[78:81]
	v_mfma_f32_16x16x32_bf16 v[130:133], v[150:153], v[168:171], v[130:133]
	v_mfma_f32_16x16x32_bf16 v[126:129], v[158:161], v[168:171], v[126:129]
	v_mfma_f32_16x16x32_bf16 v[114:117], v[150:153], v[198:201], v[114:117]
	v_mfma_f32_16x16x32_bf16 v[110:113], v[158:161], v[198:201], v[110:113]
	v_mfma_f32_16x16x32_bf16 v[98:101], v[150:153], v[210:213], v[98:101]
	v_mfma_f32_16x16x32_bf16 v[94:97], v[158:161], v[210:213], v[94:97]
	v_mfma_f32_16x16x32_bf16 v[82:85], v[150:153], v[218:221], v[82:85]
	v_mfma_f32_16x16x32_bf16 v[78:81], v[158:161], v[218:221], v[78:81]
	s_barrier
	s_mov_b32 m0, s50
	v_lshl_add_u64 v[72:73], v[238:239], 0, s[24:25]
	ds_read_b128 v[222:225], v189
	ds_read_b128 v[226:229], v190
	ds_read_b128 v[230:233], v191
	ds_read_b128 v[234:237], v192
	global_load_lds_dwordx4 v[72:73], off
	v_lshl_add_u64 v[72:73], v[240:241], 0, s[24:25]
	s_mov_b32 m0, s51
	s_nop 0
	global_load_lds_dwordx4 v[72:73], off
	s_barrier
	s_waitcnt lgkmcnt(0)
	s_waitcnt lgkmcnt(0)
	v_mfma_f32_16x16x32_bf16 v[122:125], v[222:225], v[164:167], v[122:125]
	v_mfma_f32_16x16x32_bf16 v[118:121], v[230:233], v[164:167], v[118:121]
	v_mfma_f32_16x16x32_bf16 v[106:109], v[222:225], v[194:197], v[106:109]
	v_mfma_f32_16x16x32_bf16 v[102:105], v[230:233], v[194:197], v[102:105]
	v_mfma_f32_16x16x32_bf16 v[90:93], v[222:225], v[206:209], v[90:93]
	v_mfma_f32_16x16x32_bf16 v[86:89], v[230:233], v[206:209], v[86:89]
	v_mfma_f32_16x16x32_bf16 v[72:75], v[222:225], v[214:217], v[74:77]
	v_mfma_f32_16x16x32_bf16 v[68:71], v[230:233], v[214:217], v[68:71]
	v_mfma_f32_16x16x32_bf16 v[122:125], v[226:229], v[168:171], v[122:125]
	v_mfma_f32_16x16x32_bf16 v[118:121], v[234:237], v[168:171], v[118:121]
	v_mfma_f32_16x16x32_bf16 v[106:109], v[226:229], v[198:201], v[106:109]
	v_mfma_f32_16x16x32_bf16 v[102:105], v[234:237], v[198:201], v[102:105]
	v_mfma_f32_16x16x32_bf16 v[90:93], v[226:229], v[210:213], v[90:93]
	v_mfma_f32_16x16x32_bf16 v[86:89], v[234:237], v[210:213], v[86:89]
	v_mfma_f32_16x16x32_bf16 v[74:77], v[226:229], v[218:221], v[72:75]
	v_mfma_f32_16x16x32_bf16 v[70:73], v[234:237], v[218:221], v[68:71]
	s_mov_b32 m0, s60
	s_nop 0
	v_lshl_add_u64 v[68:69], v[242:243], 0, s[24:25]
	s_barrier
	ds_read_b128 v[164:167], v174 offset:49152
	ds_read_b128 v[168:171], v174 offset:50176
	ds_read_b128 v[194:197], v174 offset:51200
	ds_read_b128 v[198:201], v174 offset:52224
	ds_read_b128 v[206:209], v174 offset:53248
	ds_read_b128 v[210:213], v174 offset:54272
	ds_read_b128 v[214:217], v174 offset:55296
	ds_read_b128 v[218:221], v174 offset:56320
	global_load_lds_dwordx4 v[68:69], off
	v_lshl_add_u64 v[68:69], v[244:245], 0, s[24:25]
	s_mov_b32 m0, s61
	s_nop 0
	global_load_lds_dwordx4 v[68:69], off
	s_barrier
	s_waitcnt lgkmcnt(0)
	s_waitcnt lgkmcnt(0)
	v_mfma_f32_16x16x32_bf16 v[62:65], v[146:149], v[164:167], v[62:65]
	v_mfma_f32_16x16x32_bf16 v[58:61], v[154:157], v[164:167], v[58:61]
	v_mfma_f32_16x16x32_bf16 v[46:49], v[146:149], v[194:197], v[46:49]
	v_mfma_f32_16x16x32_bf16 v[42:45], v[154:157], v[194:197], v[42:45]
	v_mfma_f32_16x16x32_bf16 v[30:33], v[146:149], v[206:209], v[30:33]
	v_mfma_f32_16x16x32_bf16 v[26:29], v[154:157], v[206:209], v[26:29]
	v_mfma_f32_16x16x32_bf16 v[14:17], v[146:149], v[214:217], v[14:17]
	v_mfma_f32_16x16x32_bf16 v[10:13], v[154:157], v[214:217], v[10:13]
	v_mfma_f32_16x16x32_bf16 v[62:65], v[150:153], v[168:171], v[62:65]
	v_mfma_f32_16x16x32_bf16 v[58:61], v[158:161], v[168:171], v[58:61]
	v_mfma_f32_16x16x32_bf16 v[46:49], v[150:153], v[198:201], v[46:49]
	v_mfma_f32_16x16x32_bf16 v[42:45], v[158:161], v[198:201], v[42:45]
	v_mfma_f32_16x16x32_bf16 v[30:33], v[150:153], v[210:213], v[30:33]
	v_mfma_f32_16x16x32_bf16 v[26:29], v[158:161], v[210:213], v[26:29]
	v_mfma_f32_16x16x32_bf16 v[14:17], v[150:153], v[218:221], v[14:17]
	v_mfma_f32_16x16x32_bf16 v[10:13], v[158:161], v[218:221], v[10:13]
	s_barrier
	s_mov_b32 m0, s62
	v_lshl_add_u64 v[68:69], v[246:247], 0, s[24:25]
	global_load_lds_dwordx4 v[68:69], off
	v_lshl_add_u64 v[68:69], v[248:249], 0, s[24:25]
	s_mov_b32 m0, s63
	s_nop 0
	global_load_lds_dwordx4 v[68:69], off
	s_waitcnt vmcnt(6)
	s_barrier
	v_mfma_f32_16x16x32_bf16 v[54:57], v[222:225], v[164:167], v[54:57]
	v_mfma_f32_16x16x32_bf16 v[50:53], v[230:233], v[164:167], v[50:53]
	v_mfma_f32_16x16x32_bf16 v[38:41], v[222:225], v[194:197], v[38:41]
	v_mfma_f32_16x16x32_bf16 v[34:37], v[230:233], v[194:197], v[34:37]
	v_mfma_f32_16x16x32_bf16 v[22:25], v[222:225], v[206:209], v[22:25]
	v_mfma_f32_16x16x32_bf16 v[18:21], v[230:233], v[206:209], v[18:21]
	v_mfma_f32_16x16x32_bf16 v[6:9], v[222:225], v[214:217], v[6:9]
	v_mfma_f32_16x16x32_bf16 v[2:5], v[230:233], v[214:217], v[2:5]
	v_mfma_f32_16x16x32_bf16 v[54:57], v[226:229], v[168:171], v[54:57]
	v_mfma_f32_16x16x32_bf16 v[50:53], v[234:237], v[168:171], v[50:53]
	v_mfma_f32_16x16x32_bf16 v[38:41], v[226:229], v[198:201], v[38:41]
	v_mfma_f32_16x16x32_bf16 v[34:37], v[234:237], v[198:201], v[34:37]
	v_mfma_f32_16x16x32_bf16 v[22:25], v[226:229], v[210:213], v[22:25]
	v_mfma_f32_16x16x32_bf16 v[18:21], v[234:237], v[210:213], v[18:21]
	v_mfma_f32_16x16x32_bf16 v[6:9], v[226:229], v[218:221], v[6:9]
	v_mfma_f32_16x16x32_bf16 v[2:5], v[234:237], v[218:221], v[2:5]
	s_add_u32 s26, s26, 0x100
	s_addc_u32 s27, s27, 0
	s_add_u32 s37, s37, 0x100
	s_addc_u32 s53, s53, 0
	s_cmp_ge_i32 s72, s49
	s_mov_b32 s2, s72
	s_barrier
	s_cbranch_scc0 .LBB0_1255
